# GEMM K-loops (all 5): LDS-DMA loads use saddr+32-bit voffset form; 16 per-iteration v_lshl_add_u64 address VALU ops in the load segments replaced by SALU base updates
# speedup vs baseline: 1.0084x; 1.0054x over previous
; #define PG8_STAGE(bufoff, gbase, voff) do { _Pragma("unroll") for (int _i = 0; _i < 2; ++_i) \
;         __builtin_amdgcn_global_load_lds((const unsigned*)((const char*)(gbase) + (voff)[_i]), (PG8_LAS unsigned*)(lds + (bufoff) + ldsw + _i * 8192), 16, 0, 0); } while (0)
; #define PG8_LDA(dst, b, h) do { _Pragma("unroll") for (int m = 0; m < 4; ++m) _Pragma("unroll") for (int k = 0; k < 2; ++k) dst[m][k] = *(const PG8_LAS bf16x8*)(lds + PG8_SA(b, h) + aoff + m * 2048 + k * 1024); } while (0)
; #define PG8_LDB(dst, b, h) do { _Pragma("unroll") for (int n = 0; n < 2; ++n) _Pragma("unroll") for (int k = 0; k < 2; ++k) dst[n][k] = *(const PG8_LAS bf16x8*)(lds + PG8_SB(b, h) + boff + n * 2048 + k * 1024); } while (0)
; #define PG8_MMA(ai, bj, At, Bt) do { __builtin_amdgcn_s_setprio(1); _Pragma("unroll") for (int m = 0; m < 4; ++m) _Pragma("unroll") for (int n = 0; n < 2; ++n) _Pragma("unroll") for (int k = 0; k < 2; ++k) \
;         acc[ai][bj][m][n] = __builtin_amdgcn_mfma_f32_16x16x32_bf16(Bt[n][k], At[m][k], acc[ai][bj][m][n], 0, 0, 0); __builtin_amdgcn_s_setprio(0); } while (0)
; #define PG8_WAIT_V(n) asm volatile("s_waitcnt vmcnt(" #n ")" ::: "memory")
; #define PG8_WAIT_L(n) asm volatile("s_waitcnt lgkmcnt(" #n ")" ::: "memory")
; template <class Epi, class Sched, bool ALIGN_EPI = false, bool SP2 = false>
; __device__ __forceinline__ void gemm_phase(PG8_LAS unsigned char* lds, const Gemm g, const Sched& S, const Epi& E) {
;     ...
;             const bool last = (t == nt - 2);
;             const char* a1 = cA + (size_t)(t + 1) * kstep;
;             const char* a2 = last ? nA : cA + (size_t)(t + 2) * kstep; const char* b2 = last ? nB : cB + (size_t)(t + 2) * kstep;
;             const char* a3 = a2 + kstep; const char* b3 = b2 + kstep;
;             if (last && has_next) S.a_ready(nxt);
;             if constexpr (SP2) {
;             PG8_LDB(B0, 0, 0); PG8_LDB(B1, 0, 1); PG8_SCHED; PG8_LDA(At, 0, 0); PG8_STAGE(PG8_SA(1, 1), a1 + hstep, voffA);
;             PG8_WAIT_V(8); PG8_WAIT_L(0); PG8_BAR; PG8_MMA(0, 0, At, B0); PG8_MMA(0, 1, At, B1); PG8_BAR; PG8_SCHED;
;             PG8_LDA(At, 0, 1); PG8_STAGE(PG8_SB(0, 0), b2, voffB); PG8_STAGE(PG8_SB(0, 1), b2 + hstep, voffB); PG8_STAGE(PG8_SA(0, 0), a2, voffA);
;             PG8_WAIT_V(8); PG8_WAIT_L(0); PG8_BAR; PG8_MMA(1, 0, At, B0); PG8_MMA(1, 1, At, B1); PG8_BAR; PG8_SCHED;
.LBB0_25:
	s_add_u32 s4, s80, 0xfff80080
	s_addc_u32 s5, s81, -1
	s_add_i32 s88, 0, 0x10000
	s_cmp_eq_u32 s87, 28
	s_cselect_b32 s53, s55, s5
	s_cselect_b32 s52, s83, s4
	s_cselect_b32 s5, s73, s86
	s_cselect_b32 s4, s84, s85
	s_add_i32 s90, 0, 0x14000
	v_add_u32_e32 v154, s88, v139
	v_add_u32_e32 v158, s90, v139
	ds_read_b128 v[142:145], v154
	ds_read_b128 v[146:149], v154 offset:1024
	ds_read_b128 v[150:153], v154 offset:2048
	ds_read_b128 v[154:157], v154 offset:3072
	ds_read_b128 v[164:167], v158
	ds_read_b128 v[168:171], v158 offset:1024
	ds_read_b128 v[172:175], v158 offset:2048
	ds_read_b128 v[176:179], v158 offset:3072
	s_add_i32 m0, s29, 0xc000
	ds_read_b128 v[180:183], v141
	ds_read_b128 v[184:187], v141 offset:1024
	ds_read_b128 v[188:191], v141 offset:2048
	ds_read_b128 v[192:195], v141 offset:3072
	ds_read_b128 v[196:199], v141 offset:4096
	ds_read_b128 v[222:225], v141 offset:5120
	ds_read_b128 v[226:229], v141 offset:6144
	ds_read_b128 v[230:233], v141 offset:7168
	global_load_lds_dwordx4 v134, s[80:81]
	s_add_i32 m0, s29, 0xe000
	s_nop 0
	global_load_lds_dwordx4 v136, s[80:81]
	s_waitcnt vmcnt(8)
	s_waitcnt lgkmcnt(0)
	s_barrier
	s_setprio 1
	s_waitcnt lgkmcnt(0)
	v_mfma_f32_16x16x32_bf16 v[124:127], v[142:145], v[180:183], v[124:127]
	v_mfma_f32_16x16x32_bf16 v[120:123], v[150:153], v[180:183], v[120:123]
	v_mfma_f32_16x16x32_bf16 v[116:119], v[142:145], v[188:191], v[116:119]
	v_mfma_f32_16x16x32_bf16 v[112:115], v[150:153], v[188:191], v[112:115]
	v_mfma_f32_16x16x32_bf16 v[100:103], v[142:145], v[196:199], v[100:103]
	v_mfma_f32_16x16x32_bf16 v[96:99], v[150:153], v[196:199], v[96:99]
	v_mfma_f32_16x16x32_bf16 v[84:87], v[142:145], v[226:229], v[84:87]
	v_mfma_f32_16x16x32_bf16 v[80:83], v[150:153], v[226:229], v[80:83]
	v_mfma_f32_16x16x32_bf16 v[124:127], v[146:149], v[184:187], v[124:127]
	v_mfma_f32_16x16x32_bf16 v[120:123], v[154:157], v[184:187], v[120:123]
	v_mfma_f32_16x16x32_bf16 v[116:119], v[146:149], v[192:195], v[116:119]
	v_mfma_f32_16x16x32_bf16 v[112:115], v[154:157], v[192:195], v[112:115]
	v_mfma_f32_16x16x32_bf16 v[100:103], v[146:149], v[222:225], v[100:103]
	v_mfma_f32_16x16x32_bf16 v[96:99], v[154:157], v[222:225], v[96:99]
	v_mfma_f32_16x16x32_bf16 v[84:87], v[146:149], v[230:233], v[84:87]
	v_mfma_f32_16x16x32_bf16 v[80:83], v[154:157], v[230:233], v[80:83]
	s_setprio 0
	s_setprio 1
	v_mfma_f32_16x16x32_bf16 v[108:111], v[164:167], v[180:183], v[108:111]
	v_mfma_f32_16x16x32_bf16 v[104:107], v[172:175], v[180:183], v[104:107]
	v_mfma_f32_16x16x32_bf16 v[92:95], v[164:167], v[188:191], v[92:95]
	v_mfma_f32_16x16x32_bf16 v[88:91], v[172:175], v[188:191], v[88:91]
	v_mfma_f32_16x16x32_bf16 v[76:79], v[164:167], v[196:199], v[76:79]
	v_mfma_f32_16x16x32_bf16 v[72:75], v[172:175], v[196:199], v[72:75]
	v_mfma_f32_16x16x32_bf16 v[68:71], v[164:167], v[226:229], v[68:71]
	v_mfma_f32_16x16x32_bf16 v[64:67], v[172:175], v[226:229], v[64:67]
	v_mfma_f32_16x16x32_bf16 v[108:111], v[168:171], v[184:187], v[108:111]
	v_mfma_f32_16x16x32_bf16 v[104:107], v[176:179], v[184:187], v[104:107]
	v_mfma_f32_16x16x32_bf16 v[92:95], v[168:171], v[192:195], v[92:95]
	v_mfma_f32_16x16x32_bf16 v[88:91], v[176:179], v[192:195], v[88:91]
	v_mfma_f32_16x16x32_bf16 v[76:79], v[168:171], v[222:225], v[76:79]
	v_mfma_f32_16x16x32_bf16 v[72:75], v[176:179], v[222:225], v[72:75]
	v_mfma_f32_16x16x32_bf16 v[68:71], v[168:171], v[230:233], v[68:71]
	v_mfma_f32_16x16x32_bf16 v[64:67], v[176:179], v[230:233], v[64:67]
	s_setprio 0
	s_barrier
	s_add_i32 s88, s88, s28
	s_mov_b32 m0, s88
	ds_read_b128 v[180:183], v141 offset:16384
	ds_read_b128 v[184:187], v141 offset:17408
	ds_read_b128 v[188:191], v141 offset:18432
	ds_read_b128 v[192:195], v141 offset:19456
	ds_read_b128 v[196:199], v141 offset:20480
	ds_read_b128 v[222:225], v141 offset:21504
	ds_read_b128 v[226:229], v141 offset:22528
	ds_read_b128 v[230:233], v141 offset:23552
	global_load_lds_dwordx4 v160, s[4:5]
	s_add_i32 m0, s88, 0x2000
	s_add_u32 s88, s4, 0x80000
	s_addc_u32 s89, s5, 0
	s_add_i32 s90, s90, s28
	global_load_lds_dwordx4 v128, s[4:5]
	s_mov_b32 m0, s90
	s_nop 0
	global_load_lds_dwordx4 v160, s[88:89]
	s_add_i32 m0, s90, 0x2000
	s_nop 0
	global_load_lds_dwordx4 v128, s[88:89]
	s_mov_b32 m0, s29
	s_nop 0
	global_load_lds_dwordx4 v132, s[52:53]
	s_mov_b32 m0, s45
	s_nop 0
	global_load_lds_dwordx4 v130, s[52:53]
	s_add_u32 s98, s52, 0x80
	s_addc_u32 s99, s53, 0
	s_waitcnt vmcnt(8)
	s_waitcnt lgkmcnt(0)
	s_barrier
	s_setprio 1
	s_waitcnt lgkmcnt(0)
	v_mfma_f32_16x16x32_bf16 v[60:63], v[142:145], v[180:183], v[60:63]
	v_mfma_f32_16x16x32_bf16 v[56:59], v[150:153], v[180:183], v[56:59]
	v_mfma_f32_16x16x32_bf16 v[52:55], v[142:145], v[188:191], v[52:55]
	v_mfma_f32_16x16x32_bf16 v[48:51], v[150:153], v[188:191], v[48:51]
	v_mfma_f32_16x16x32_bf16 v[36:39], v[142:145], v[196:199], v[36:39]
	v_mfma_f32_16x16x32_bf16 v[32:35], v[150:153], v[196:199], v[32:35]
	v_mfma_f32_16x16x32_bf16 v[20:23], v[142:145], v[226:229], v[20:23]
	v_mfma_f32_16x16x32_bf16 v[16:19], v[150:153], v[226:229], v[16:19]
	v_mfma_f32_16x16x32_bf16 v[60:63], v[146:149], v[184:187], v[60:63]
	v_mfma_f32_16x16x32_bf16 v[56:59], v[154:157], v[184:187], v[56:59]
	v_mfma_f32_16x16x32_bf16 v[52:55], v[146:149], v[192:195], v[52:55]
	v_mfma_f32_16x16x32_bf16 v[48:51], v[154:157], v[192:195], v[48:51]
	v_mfma_f32_16x16x32_bf16 v[36:39], v[146:149], v[222:225], v[36:39]
	v_mfma_f32_16x16x32_bf16 v[32:35], v[154:157], v[222:225], v[32:35]
	v_mfma_f32_16x16x32_bf16 v[20:23], v[146:149], v[230:233], v[20:23]
	v_mfma_f32_16x16x32_bf16 v[16:19], v[154:157], v[230:233], v[16:19]
	s_setprio 0
	s_setprio 1
	v_mfma_f32_16x16x32_bf16 v[44:47], v[164:167], v[180:183], v[44:47]
	v_mfma_f32_16x16x32_bf16 v[40:43], v[172:175], v[180:183], v[40:43]
	v_mfma_f32_16x16x32_bf16 v[28:31], v[164:167], v[188:191], v[28:31]
	v_mfma_f32_16x16x32_bf16 v[24:27], v[172:175], v[188:191], v[24:27]
	v_mfma_f32_16x16x32_bf16 v[12:15], v[164:167], v[196:199], v[12:15]
	v_mfma_f32_16x16x32_bf16 v[8:11], v[172:175], v[196:199], v[8:11]
	v_mfma_f32_16x16x32_bf16 v[4:7], v[164:167], v[226:229], v[4:7]
	v_mfma_f32_16x16x32_bf16 v[0:3], v[172:175], v[226:229], v[0:3]
	v_mfma_f32_16x16x32_bf16 v[44:47], v[168:171], v[184:187], v[44:47]
	v_mfma_f32_16x16x32_bf16 v[40:43], v[176:179], v[184:187], v[40:43]
	v_mfma_f32_16x16x32_bf16 v[28:31], v[168:171], v[192:195], v[28:31]
	v_mfma_f32_16x16x32_bf16 v[24:27], v[176:179], v[192:195], v[24:27]
	v_mfma_f32_16x16x32_bf16 v[12:15], v[168:171], v[222:225], v[12:15]
	v_mfma_f32_16x16x32_bf16 v[8:11], v[176:179], v[222:225], v[8:11]
	v_mfma_f32_16x16x32_bf16 v[4:7], v[168:171], v[230:233], v[4:7]
	v_mfma_f32_16x16x32_bf16 v[0:3], v[176:179], v[230:233], v[0:3]
	s_setprio 0
	s_barrier
; #define PG8_STAGE(bufoff, gbase, voff) do { _Pragma("unroll") for (int _i = 0; _i < 2; ++_i) \
;         __builtin_amdgcn_global_load_lds((const unsigned*)((const char*)(gbase) + (voff)[_i]), (PG8_LAS unsigned*)(lds + (bufoff) + ldsw + _i * 8192), 16, 0, 0); } while (0)
; #define PG8_LDA(dst, b, h) do { _Pragma("unroll") for (int m = 0; m < 4; ++m) _Pragma("unroll") for (int k = 0; k < 2; ++k) dst[m][k] = *(const PG8_LAS bf16x8*)(lds + PG8_SA(b, h) + aoff + m * 2048 + k * 1024); } while (0)
; #define PG8_LDB(dst, b, h) do { _Pragma("unroll") for (int n = 0; n < 2; ++n) _Pragma("unroll") for (int k = 0; k < 2; ++k) dst[n][k] = *(const PG8_LAS bf16x8*)(lds + PG8_SB(b, h) + boff + n * 2048 + k * 1024); } while (0)
; #define PG8_MMA(ai, bj, At, Bt) do { __builtin_amdgcn_s_setprio(1); _Pragma("unroll") for (int m = 0; m < 4; ++m) _Pragma("unroll") for (int n = 0; n < 2; ++n) _Pragma("unroll") for (int k = 0; k < 2; ++k) \
;         acc[ai][bj][m][n] = __builtin_amdgcn_mfma_f32_16x16x32_bf16(Bt[n][k], At[m][k], acc[ai][bj][m][n], 0, 0, 0); __builtin_amdgcn_s_setprio(0); } while (0)
; #define PG8_WAIT_V(n) asm volatile("s_waitcnt vmcnt(" #n ")" ::: "memory")
; #define PG8_WAIT_L(n) asm volatile("s_waitcnt lgkmcnt(" #n ")" ::: "memory")
; #define PG8_BAR __builtin_amdgcn_s_barrier()
; #define PG8_SCHED __builtin_amdgcn_sched_barrier(0)
; template <class Epi, class Sched, bool ALIGN_EPI = false, bool SP2 = false>
; __device__ __forceinline__ void gemm_phase(PG8_LAS unsigned char* lds, const Gemm g, const Sched& S, const Epi& E) {
;     ...
;             PG8_LDB(B0, 1, 0); PG8_LDB(B1, 1, 1); PG8_SCHED; PG8_LDA(At, 1, 0); PG8_STAGE(PG8_SA(0, 1), a2 + hstep, voffA);
;             PG8_WAIT_V(8); PG8_WAIT_L(0); PG8_BAR; PG8_MMA(0, 0, At, B0); PG8_MMA(0, 1, At, B1); PG8_BAR; PG8_SCHED;
;             PG8_LDA(At, 1, 1); PG8_STAGE(PG8_SB(1, 0), b3, voffB); PG8_STAGE(PG8_SB(1, 1), b3 + hstep, voffB); PG8_STAGE(PG8_SA(1, 0), a3, voffA);
;             PG8_WAIT_V(8); PG8_WAIT_L(0); PG8_BAR; PG8_MMA(1, 0, At, B0); PG8_MMA(1, 1, At, B1); PG8_BAR; PG8_SCHED;
	s_add_i32 s88, 0, 0x18000
	s_add_i32 s89, 0, 0x1c000
	v_add_u32_e32 v154, s88, v139
	v_add_u32_e32 v163, s89, v139
	ds_read_b128 v[142:145], v154
	ds_read_b128 v[146:149], v154 offset:1024
	ds_read_b128 v[150:153], v154 offset:2048
	ds_read_b128 v[154:157], v154 offset:3072
	ds_read_b128 v[164:167], v163
	ds_read_b128 v[168:171], v163 offset:1024
	ds_read_b128 v[172:175], v163 offset:2048
	ds_read_b128 v[176:179], v163 offset:3072
	s_add_u32 s52, s52, 0x80000
	s_addc_u32 s53, s53, 0
	s_mov_b32 m0, s56
	ds_read_b128 v[180:183], v141 offset:32768
	ds_read_b128 v[184:187], v141 offset:33792
	ds_read_b128 v[188:191], v141 offset:34816
	ds_read_b128 v[192:195], v141 offset:35840
	ds_read_b128 v[196:199], v141 offset:36864
	ds_read_b128 v[222:225], v141 offset:37888
	ds_read_b128 v[226:229], v141 offset:38912
	ds_read_b128 v[230:233], v141 offset:39936
	global_load_lds_dwordx4 v132, s[52:53]
	s_mov_b32 m0, s57
	s_nop 0
	global_load_lds_dwordx4 v130, s[52:53]
	s_waitcnt vmcnt(8)
	s_waitcnt lgkmcnt(0)
	s_barrier
	s_setprio 1
	s_waitcnt lgkmcnt(0)
	v_mfma_f32_16x16x32_bf16 v[124:127], v[142:145], v[180:183], v[124:127]
	v_mfma_f32_16x16x32_bf16 v[120:123], v[150:153], v[180:183], v[120:123]
	v_mfma_f32_16x16x32_bf16 v[116:119], v[142:145], v[188:191], v[116:119]
	v_mfma_f32_16x16x32_bf16 v[112:115], v[150:153], v[188:191], v[112:115]
	v_mfma_f32_16x16x32_bf16 v[100:103], v[142:145], v[196:199], v[100:103]
	v_mfma_f32_16x16x32_bf16 v[96:99], v[150:153], v[196:199], v[96:99]
	v_mfma_f32_16x16x32_bf16 v[84:87], v[142:145], v[226:229], v[84:87]
	v_mfma_f32_16x16x32_bf16 v[80:83], v[150:153], v[226:229], v[80:83]
	v_mfma_f32_16x16x32_bf16 v[124:127], v[146:149], v[184:187], v[124:127]
	v_mfma_f32_16x16x32_bf16 v[120:123], v[154:157], v[184:187], v[120:123]
	v_mfma_f32_16x16x32_bf16 v[116:119], v[146:149], v[192:195], v[116:119]
	v_mfma_f32_16x16x32_bf16 v[112:115], v[154:157], v[192:195], v[112:115]
	v_mfma_f32_16x16x32_bf16 v[100:103], v[146:149], v[222:225], v[100:103]
	v_mfma_f32_16x16x32_bf16 v[96:99], v[154:157], v[222:225], v[96:99]
	v_mfma_f32_16x16x32_bf16 v[84:87], v[146:149], v[230:233], v[84:87]
	v_mfma_f32_16x16x32_bf16 v[80:83], v[154:157], v[230:233], v[80:83]
	s_setprio 0
	s_setprio 1
	v_mfma_f32_16x16x32_bf16 v[108:111], v[164:167], v[180:183], v[108:111]
	v_mfma_f32_16x16x32_bf16 v[104:107], v[172:175], v[180:183], v[104:107]
	v_mfma_f32_16x16x32_bf16 v[92:95], v[164:167], v[188:191], v[92:95]
	v_mfma_f32_16x16x32_bf16 v[88:91], v[172:175], v[188:191], v[88:91]
	v_mfma_f32_16x16x32_bf16 v[76:79], v[164:167], v[196:199], v[76:79]
	v_mfma_f32_16x16x32_bf16 v[72:75], v[172:175], v[196:199], v[72:75]
	v_mfma_f32_16x16x32_bf16 v[68:71], v[164:167], v[226:229], v[68:71]
	v_mfma_f32_16x16x32_bf16 v[64:67], v[172:175], v[226:229], v[64:67]
	v_mfma_f32_16x16x32_bf16 v[108:111], v[168:171], v[184:187], v[108:111]
	v_mfma_f32_16x16x32_bf16 v[104:107], v[176:179], v[184:187], v[104:107]
	v_mfma_f32_16x16x32_bf16 v[92:95], v[168:171], v[192:195], v[92:95]
	v_mfma_f32_16x16x32_bf16 v[88:91], v[176:179], v[192:195], v[88:91]
	v_mfma_f32_16x16x32_bf16 v[76:79], v[168:171], v[222:225], v[76:79]
	v_mfma_f32_16x16x32_bf16 v[72:75], v[176:179], v[222:225], v[72:75]
	v_mfma_f32_16x16x32_bf16 v[68:71], v[168:171], v[230:233], v[68:71]
	v_mfma_f32_16x16x32_bf16 v[64:67], v[176:179], v[230:233], v[64:67]
	s_setprio 0
	s_barrier
	s_add_i32 s52, s88, s28
	s_mov_b32 m0, s52
	ds_read_b128 v[180:183], v141 offset:49152
	ds_read_b128 v[184:187], v141 offset:50176
	ds_read_b128 v[188:191], v141 offset:51200
	ds_read_b128 v[192:195], v141 offset:52224
	ds_read_b128 v[196:199], v141 offset:53248
	ds_read_b128 v[222:225], v141 offset:54272
	ds_read_b128 v[226:229], v141 offset:55296
	ds_read_b128 v[230:233], v141 offset:56320
	s_add_u32 s4, s4, 0x80
	s_addc_u32 s5, s5, 0
	global_load_lds_dwordx4 v160, s[4:5]
	s_add_i32 m0, s52, 0x2000
	s_add_i32 s52, s89, s28
	global_load_lds_dwordx4 v128, s[4:5]
	s_add_u32 s4, s4, 0x80000
	s_addc_u32 s5, s5, 0
	s_mov_b32 m0, s52
	s_nop 0
	global_load_lds_dwordx4 v160, s[4:5]
	s_add_i32 m0, s52, 0x2000
	s_nop 0
	global_load_lds_dwordx4 v128, s[4:5]
	s_mov_b32 m0, s24
	s_nop 0
	global_load_lds_dwordx4 v132, s[98:99]
	s_mov_b32 m0, s59
	s_nop 0
	global_load_lds_dwordx4 v130, s[98:99]
	s_waitcnt vmcnt(8)
	s_waitcnt lgkmcnt(0)
	s_barrier
	s_setprio 1
	s_waitcnt lgkmcnt(0)
	v_mfma_f32_16x16x32_bf16 v[60:63], v[142:145], v[180:183], v[60:63]
	v_mfma_f32_16x16x32_bf16 v[56:59], v[150:153], v[180:183], v[56:59]
	v_mfma_f32_16x16x32_bf16 v[52:55], v[142:145], v[188:191], v[52:55]
	v_mfma_f32_16x16x32_bf16 v[48:51], v[150:153], v[188:191], v[48:51]
	v_mfma_f32_16x16x32_bf16 v[36:39], v[142:145], v[196:199], v[36:39]
	v_mfma_f32_16x16x32_bf16 v[32:35], v[150:153], v[196:199], v[32:35]
	v_mfma_f32_16x16x32_bf16 v[20:23], v[142:145], v[226:229], v[20:23]
	v_mfma_f32_16x16x32_bf16 v[16:19], v[150:153], v[226:229], v[16:19]
	v_mfma_f32_16x16x32_bf16 v[60:63], v[146:149], v[184:187], v[60:63]
	v_mfma_f32_16x16x32_bf16 v[56:59], v[154:157], v[184:187], v[56:59]
	v_mfma_f32_16x16x32_bf16 v[52:55], v[146:149], v[192:195], v[52:55]
	v_mfma_f32_16x16x32_bf16 v[48:51], v[154:157], v[192:195], v[48:51]
	v_mfma_f32_16x16x32_bf16 v[36:39], v[146:149], v[222:225], v[36:39]
	v_mfma_f32_16x16x32_bf16 v[32:35], v[154:157], v[222:225], v[32:35]
	v_mfma_f32_16x16x32_bf16 v[20:23], v[146:149], v[230:233], v[20:23]
	v_mfma_f32_16x16x32_bf16 v[16:19], v[154:157], v[230:233], v[16:19]
	s_setprio 0
	s_setprio 1
	v_mfma_f32_16x16x32_bf16 v[44:47], v[164:167], v[180:183], v[44:47]
	v_mfma_f32_16x16x32_bf16 v[40:43], v[172:175], v[180:183], v[40:43]
	v_mfma_f32_16x16x32_bf16 v[28:31], v[164:167], v[188:191], v[28:31]
	v_mfma_f32_16x16x32_bf16 v[24:27], v[172:175], v[188:191], v[24:27]
	v_mfma_f32_16x16x32_bf16 v[12:15], v[164:167], v[196:199], v[12:15]
	v_mfma_f32_16x16x32_bf16 v[8:11], v[172:175], v[196:199], v[8:11]
	v_mfma_f32_16x16x32_bf16 v[4:7], v[164:167], v[226:229], v[4:7]
	v_mfma_f32_16x16x32_bf16 v[0:3], v[172:175], v[226:229], v[0:3]
	v_mfma_f32_16x16x32_bf16 v[44:47], v[168:171], v[184:187], v[44:47]
	v_mfma_f32_16x16x32_bf16 v[40:43], v[176:179], v[184:187], v[40:43]
	v_mfma_f32_16x16x32_bf16 v[28:31], v[168:171], v[192:195], v[28:31]
	v_mfma_f32_16x16x32_bf16 v[24:27], v[176:179], v[192:195], v[24:27]
	v_mfma_f32_16x16x32_bf16 v[12:15], v[168:171], v[222:225], v[12:15]
	v_mfma_f32_16x16x32_bf16 v[8:11], v[176:179], v[222:225], v[8:11]
	v_mfma_f32_16x16x32_bf16 v[4:7], v[168:171], v[230:233], v[4:7]
	v_mfma_f32_16x16x32_bf16 v[0:3], v[176:179], v[230:233], v[0:3]
	s_setprio 0
	s_barrier
	s_add_i32 s87, s87, 2
	s_add_u32 s80, s80, 0x100
	s_addc_u32 s81, s81, 0
	s_add_u32 s85, s85, 0x100
	s_addc_u32 s86, s86, 0
	s_cmp_gt_u32 s87, 29
	s_cbranch_scc0 .LBB0_25
	s_and_b64 vcc, exec, s[42:43]
	s_cbranch_vccz .LBB0_28
	s_barrier

; #define PG8_STAGE(bufoff, gbase, voff) do { _Pragma("unroll") for (int _i = 0; _i < 2; ++_i) \
;         __builtin_amdgcn_global_load_lds((const unsigned*)((const char*)(gbase) + (voff)[_i]), (PG8_LAS unsigned*)(lds + (bufoff) + ldsw + _i * 8192), 16, 0, 0); } while (0)
; #define PG8_LDA(dst, b, h) do { _Pragma("unroll") for (int m = 0; m < 4; ++m) _Pragma("unroll") for (int k = 0; k < 2; ++k) dst[m][k] = *(const PG8_LAS bf16x8*)(lds + PG8_SA(b, h) + aoff + m * 2048 + k * 1024); } while (0)
; #define PG8_LDB(dst, b, h) do { _Pragma("unroll") for (int n = 0; n < 2; ++n) _Pragma("unroll") for (int k = 0; k < 2; ++k) dst[n][k] = *(const PG8_LAS bf16x8*)(lds + PG8_SB(b, h) + boff + n * 2048 + k * 1024); } while (0)
; #define PG8_MMA(ai, bj, At, Bt) do { __builtin_amdgcn_s_setprio(1); _Pragma("unroll") for (int m = 0; m < 4; ++m) _Pragma("unroll") for (int n = 0; n < 2; ++n) _Pragma("unroll") for (int k = 0; k < 2; ++k) \
;         acc[ai][bj][m][n] = __builtin_amdgcn_mfma_f32_16x16x32_bf16(Bt[n][k], At[m][k], acc[ai][bj][m][n], 0, 0, 0); __builtin_amdgcn_s_setprio(0); } while (0)
; #define PG8_WAIT_V(n) asm volatile("s_waitcnt vmcnt(" #n ")" ::: "memory")
; #define PG8_WAIT_L(n) asm volatile("s_waitcnt lgkmcnt(" #n ")" ::: "memory")
; template <class Epi, class Sched, bool ALIGN_EPI = false, bool SP2 = false>
; __device__ __forceinline__ void gemm_phase(PG8_LAS unsigned char* lds, const Gemm g, const Sched& S, const Epi& E) {
;     ...
;             const bool last = (t == nt - 2);
;             const char* a1 = cA + (size_t)(t + 1) * kstep;
;             const char* a2 = last ? nA : cA + (size_t)(t + 2) * kstep; const char* b2 = last ? nB : cB + (size_t)(t + 2) * kstep;
;             const char* a3 = a2 + kstep; const char* b3 = b2 + kstep;
;             if (last && has_next) S.a_ready(nxt);
;             if constexpr (SP2) {
;             PG8_LDB(B0, 0, 0); PG8_LDB(B1, 0, 1); PG8_SCHED; PG8_LDA(At, 0, 0); PG8_STAGE(PG8_SA(1, 1), a1 + hstep, voffA);
;             PG8_WAIT_V(8); PG8_WAIT_L(0); PG8_BAR; PG8_MMA(0, 0, At, B0); PG8_MMA(0, 1, At, B1); PG8_BAR; PG8_SCHED;
;             PG8_LDA(At, 0, 1); PG8_STAGE(PG8_SB(0, 0), b2, voffB); PG8_STAGE(PG8_SB(0, 1), b2 + hstep, voffB); PG8_STAGE(PG8_SA(0, 0), a2, voffA);
;             PG8_WAIT_V(8); PG8_WAIT_L(0); PG8_BAR; PG8_MMA(1, 0, At, B0); PG8_MMA(1, 1, At, B1); PG8_BAR; PG8_SCHED;
.LBB0_52:
	s_add_u32 s4, s72, 0x100
	s_addc_u32 s5, s73, 0
	s_add_i32 s84, 0, 0x10000
	s_cmpk_eq_i32 s83, 0x54
	s_cselect_b32 s57, s45, s5
	s_cselect_b32 s56, s44, s4
	s_cselect_b32 s53, s55, s82
	s_cselect_b32 s52, s54, s81
	s_add_i32 s85, 0, 0x14000
	v_add_u32_e32 v154, s84, v139
	v_add_u32_e32 v158, s85, v139
	ds_read_b128 v[142:145], v154
	ds_read_b128 v[146:149], v154 offset:1024
	ds_read_b128 v[150:153], v154 offset:2048
	ds_read_b128 v[154:157], v154 offset:3072
	ds_read_b128 v[164:167], v158
	ds_read_b128 v[168:171], v158 offset:1024
	ds_read_b128 v[172:175], v158 offset:2048
	ds_read_b128 v[176:179], v158 offset:3072
	s_add_i32 m0, s28, 0xc000
	ds_read_b128 v[180:183], v141
	ds_read_b128 v[184:187], v141 offset:1024
	ds_read_b128 v[188:191], v141 offset:2048
	ds_read_b128 v[192:195], v141 offset:3072
	ds_read_b128 v[196:199], v141 offset:4096
	ds_read_b128 v[222:225], v141 offset:5120
	ds_read_b128 v[226:229], v141 offset:6144
	ds_read_b128 v[230:233], v141 offset:7168
	global_load_lds_dwordx4 v134, s[72:73]
	s_add_i32 m0, s28, 0xe000
	s_nop 0
	global_load_lds_dwordx4 v136, s[72:73]
	s_waitcnt vmcnt(8)
	s_waitcnt lgkmcnt(0)
	s_barrier
	s_setprio 1
	s_waitcnt lgkmcnt(0)
	v_mfma_f32_16x16x32_bf16 v[124:127], v[142:145], v[180:183], v[124:127]
	v_mfma_f32_16x16x32_bf16 v[120:123], v[150:153], v[180:183], v[120:123]
	v_mfma_f32_16x16x32_bf16 v[116:119], v[142:145], v[188:191], v[116:119]
	v_mfma_f32_16x16x32_bf16 v[112:115], v[150:153], v[188:191], v[112:115]
	v_mfma_f32_16x16x32_bf16 v[100:103], v[142:145], v[196:199], v[100:103]
	v_mfma_f32_16x16x32_bf16 v[96:99], v[150:153], v[196:199], v[96:99]
	v_mfma_f32_16x16x32_bf16 v[84:87], v[142:145], v[226:229], v[84:87]
	v_mfma_f32_16x16x32_bf16 v[80:83], v[150:153], v[226:229], v[80:83]
	v_mfma_f32_16x16x32_bf16 v[124:127], v[146:149], v[184:187], v[124:127]
	v_mfma_f32_16x16x32_bf16 v[120:123], v[154:157], v[184:187], v[120:123]
	v_mfma_f32_16x16x32_bf16 v[116:119], v[146:149], v[192:195], v[116:119]
	v_mfma_f32_16x16x32_bf16 v[112:115], v[154:157], v[192:195], v[112:115]
	v_mfma_f32_16x16x32_bf16 v[100:103], v[146:149], v[222:225], v[100:103]
	v_mfma_f32_16x16x32_bf16 v[96:99], v[154:157], v[222:225], v[96:99]
	v_mfma_f32_16x16x32_bf16 v[84:87], v[146:149], v[230:233], v[84:87]
	v_mfma_f32_16x16x32_bf16 v[80:83], v[154:157], v[230:233], v[80:83]
	s_setprio 0
	s_setprio 1
	v_mfma_f32_16x16x32_bf16 v[108:111], v[164:167], v[180:183], v[108:111]
	v_mfma_f32_16x16x32_bf16 v[104:107], v[172:175], v[180:183], v[104:107]
	v_mfma_f32_16x16x32_bf16 v[92:95], v[164:167], v[188:191], v[92:95]
	v_mfma_f32_16x16x32_bf16 v[88:91], v[172:175], v[188:191], v[88:91]
	v_mfma_f32_16x16x32_bf16 v[76:79], v[164:167], v[196:199], v[76:79]
	v_mfma_f32_16x16x32_bf16 v[72:75], v[172:175], v[196:199], v[72:75]
	v_mfma_f32_16x16x32_bf16 v[68:71], v[164:167], v[226:229], v[68:71]
	v_mfma_f32_16x16x32_bf16 v[64:67], v[172:175], v[226:229], v[64:67]
	v_mfma_f32_16x16x32_bf16 v[108:111], v[168:171], v[184:187], v[108:111]
	v_mfma_f32_16x16x32_bf16 v[104:107], v[176:179], v[184:187], v[104:107]
	v_mfma_f32_16x16x32_bf16 v[92:95], v[168:171], v[192:195], v[92:95]
	v_mfma_f32_16x16x32_bf16 v[88:91], v[176:179], v[192:195], v[88:91]
	v_mfma_f32_16x16x32_bf16 v[76:79], v[168:171], v[222:225], v[76:79]
	v_mfma_f32_16x16x32_bf16 v[72:75], v[176:179], v[222:225], v[72:75]
	v_mfma_f32_16x16x32_bf16 v[68:71], v[168:171], v[230:233], v[68:71]
	v_mfma_f32_16x16x32_bf16 v[64:67], v[176:179], v[230:233], v[64:67]
	s_setprio 0
	s_barrier
	s_add_i32 s72, s84, s24
	s_mov_b32 m0, s72
	ds_read_b128 v[180:183], v141 offset:16384
	ds_read_b128 v[184:187], v141 offset:17408
	ds_read_b128 v[188:191], v141 offset:18432
	ds_read_b128 v[192:195], v141 offset:19456
	ds_read_b128 v[196:199], v141 offset:20480
	ds_read_b128 v[222:225], v141 offset:21504
	ds_read_b128 v[226:229], v141 offset:22528
	ds_read_b128 v[230:233], v141 offset:23552
	global_load_lds_dwordx4 v160, s[52:53]
	s_add_i32 m0, s72, 0x2000
	s_add_u32 s72, s52, 0x160000
	s_addc_u32 s73, s53, 0
	s_add_i32 s84, s85, s24
	global_load_lds_dwordx4 v128, s[52:53]
	s_mov_b32 m0, s84
	s_nop 0
	global_load_lds_dwordx4 v160, s[72:73]
	s_add_i32 m0, s84, 0x2000
	s_nop 0
	global_load_lds_dwordx4 v128, s[72:73]
	s_mov_b32 m0, s28
	s_nop 0
	global_load_lds_dwordx4 v132, s[56:57]
	s_mov_b32 m0, s29
	s_nop 0
	global_load_lds_dwordx4 v130, s[56:57]
	s_add_u32 s98, s56, 0x80
	s_addc_u32 s99, s57, 0
	s_waitcnt vmcnt(8)
	s_waitcnt lgkmcnt(0)
	s_barrier
	s_setprio 1
	s_waitcnt lgkmcnt(0)
	v_mfma_f32_16x16x32_bf16 v[60:63], v[142:145], v[180:183], v[60:63]
	v_mfma_f32_16x16x32_bf16 v[56:59], v[150:153], v[180:183], v[56:59]
	v_mfma_f32_16x16x32_bf16 v[52:55], v[142:145], v[188:191], v[52:55]
	v_mfma_f32_16x16x32_bf16 v[48:51], v[150:153], v[188:191], v[48:51]
	v_mfma_f32_16x16x32_bf16 v[36:39], v[142:145], v[196:199], v[36:39]
	v_mfma_f32_16x16x32_bf16 v[32:35], v[150:153], v[196:199], v[32:35]
	v_mfma_f32_16x16x32_bf16 v[20:23], v[142:145], v[226:229], v[20:23]
	v_mfma_f32_16x16x32_bf16 v[16:19], v[150:153], v[226:229], v[16:19]
	v_mfma_f32_16x16x32_bf16 v[60:63], v[146:149], v[184:187], v[60:63]
	v_mfma_f32_16x16x32_bf16 v[56:59], v[154:157], v[184:187], v[56:59]
	v_mfma_f32_16x16x32_bf16 v[52:55], v[146:149], v[192:195], v[52:55]
	v_mfma_f32_16x16x32_bf16 v[48:51], v[154:157], v[192:195], v[48:51]
	v_mfma_f32_16x16x32_bf16 v[36:39], v[146:149], v[222:225], v[36:39]
	v_mfma_f32_16x16x32_bf16 v[32:35], v[154:157], v[222:225], v[32:35]
	v_mfma_f32_16x16x32_bf16 v[20:23], v[146:149], v[230:233], v[20:23]
	v_mfma_f32_16x16x32_bf16 v[16:19], v[154:157], v[230:233], v[16:19]
	s_setprio 0
	s_setprio 1
	v_mfma_f32_16x16x32_bf16 v[44:47], v[164:167], v[180:183], v[44:47]
	v_mfma_f32_16x16x32_bf16 v[40:43], v[172:175], v[180:183], v[40:43]
	v_mfma_f32_16x16x32_bf16 v[28:31], v[164:167], v[188:191], v[28:31]
	v_mfma_f32_16x16x32_bf16 v[24:27], v[172:175], v[188:191], v[24:27]
	v_mfma_f32_16x16x32_bf16 v[12:15], v[164:167], v[196:199], v[12:15]
	v_mfma_f32_16x16x32_bf16 v[8:11], v[172:175], v[196:199], v[8:11]
	v_mfma_f32_16x16x32_bf16 v[4:7], v[164:167], v[226:229], v[4:7]
	v_mfma_f32_16x16x32_bf16 v[0:3], v[172:175], v[226:229], v[0:3]
	v_mfma_f32_16x16x32_bf16 v[44:47], v[168:171], v[184:187], v[44:47]
	v_mfma_f32_16x16x32_bf16 v[40:43], v[176:179], v[184:187], v[40:43]
	v_mfma_f32_16x16x32_bf16 v[28:31], v[168:171], v[192:195], v[28:31]
	v_mfma_f32_16x16x32_bf16 v[24:27], v[176:179], v[192:195], v[24:27]
	v_mfma_f32_16x16x32_bf16 v[12:15], v[168:171], v[222:225], v[12:15]
	v_mfma_f32_16x16x32_bf16 v[8:11], v[176:179], v[222:225], v[8:11]
	v_mfma_f32_16x16x32_bf16 v[4:7], v[168:171], v[230:233], v[4:7]
	v_mfma_f32_16x16x32_bf16 v[0:3], v[176:179], v[230:233], v[0:3]
	s_setprio 0
	s_barrier
; #define PG8_STAGE(bufoff, gbase, voff) do { _Pragma("unroll") for (int _i = 0; _i < 2; ++_i) \
;         __builtin_amdgcn_global_load_lds((const unsigned*)((const char*)(gbase) + (voff)[_i]), (PG8_LAS unsigned*)(lds + (bufoff) + ldsw + _i * 8192), 16, 0, 0); } while (0)
; #define PG8_LDA(dst, b, h) do { _Pragma("unroll") for (int m = 0; m < 4; ++m) _Pragma("unroll") for (int k = 0; k < 2; ++k) dst[m][k] = *(const PG8_LAS bf16x8*)(lds + PG8_SA(b, h) + aoff + m * 2048 + k * 1024); } while (0)
; #define PG8_LDB(dst, b, h) do { _Pragma("unroll") for (int n = 0; n < 2; ++n) _Pragma("unroll") for (int k = 0; k < 2; ++k) dst[n][k] = *(const PG8_LAS bf16x8*)(lds + PG8_SB(b, h) + boff + n * 2048 + k * 1024); } while (0)
; #define PG8_MMA(ai, bj, At, Bt) do { __builtin_amdgcn_s_setprio(1); _Pragma("unroll") for (int m = 0; m < 4; ++m) _Pragma("unroll") for (int n = 0; n < 2; ++n) _Pragma("unroll") for (int k = 0; k < 2; ++k) \
;         acc[ai][bj][m][n] = __builtin_amdgcn_mfma_f32_16x16x32_bf16(Bt[n][k], At[m][k], acc[ai][bj][m][n], 0, 0, 0); __builtin_amdgcn_s_setprio(0); } while (0)
; #define PG8_WAIT_V(n) asm volatile("s_waitcnt vmcnt(" #n ")" ::: "memory")
; #define PG8_WAIT_L(n) asm volatile("s_waitcnt lgkmcnt(" #n ")" ::: "memory")
; #define PG8_BAR __builtin_amdgcn_s_barrier()
; #define PG8_SCHED __builtin_amdgcn_sched_barrier(0)
; template <class Epi, class Sched, bool ALIGN_EPI = false, bool SP2 = false>
; __device__ __forceinline__ void gemm_phase(PG8_LAS unsigned char* lds, const Gemm g, const Sched& S, const Epi& E) {
;     ...
;             PG8_LDB(B0, 1, 0); PG8_LDB(B1, 1, 1); PG8_SCHED; PG8_LDA(At, 1, 0); PG8_STAGE(PG8_SA(0, 1), a2 + hstep, voffA);
;             PG8_WAIT_V(8); PG8_WAIT_L(0); PG8_BAR; PG8_MMA(0, 0, At, B0); PG8_MMA(0, 1, At, B1); PG8_BAR; PG8_SCHED;
;             PG8_LDA(At, 1, 1); PG8_STAGE(PG8_SB(1, 0), b3, voffB); PG8_STAGE(PG8_SB(1, 1), b3 + hstep, voffB); PG8_STAGE(PG8_SA(1, 0), a3, voffA);
;             PG8_WAIT_V(8); PG8_WAIT_L(0); PG8_BAR; PG8_MMA(1, 0, At, B0); PG8_MMA(1, 1, At, B1); PG8_BAR; PG8_SCHED;
	s_add_i32 s72, 0, 0x18000
	s_add_i32 s73, 0, 0x1c000
	v_add_u32_e32 v154, s72, v139
	v_add_u32_e32 v163, s73, v139
	ds_read_b128 v[142:145], v154
	ds_read_b128 v[146:149], v154 offset:1024
	ds_read_b128 v[150:153], v154 offset:2048
	ds_read_b128 v[154:157], v154 offset:3072
	ds_read_b128 v[164:167], v163
	ds_read_b128 v[168:171], v163 offset:1024
	ds_read_b128 v[172:175], v163 offset:2048
	ds_read_b128 v[176:179], v163 offset:3072
	s_add_u32 s56, s56, 0x160000
	s_addc_u32 s57, s57, 0
	s_mov_b32 m0, s59
	ds_read_b128 v[180:183], v141 offset:32768
	ds_read_b128 v[184:187], v141 offset:33792
	ds_read_b128 v[188:191], v141 offset:34816
	ds_read_b128 v[192:195], v141 offset:35840
	ds_read_b128 v[196:199], v141 offset:36864
	ds_read_b128 v[222:225], v141 offset:37888
	ds_read_b128 v[226:229], v141 offset:38912
	ds_read_b128 v[230:233], v141 offset:39936
	global_load_lds_dwordx4 v132, s[56:57]
	s_mov_b32 m0, s63
	s_nop 0
	global_load_lds_dwordx4 v130, s[56:57]
	s_waitcnt vmcnt(8)
	s_waitcnt lgkmcnt(0)
	s_barrier
	s_setprio 1
	s_waitcnt lgkmcnt(0)
	v_mfma_f32_16x16x32_bf16 v[124:127], v[142:145], v[180:183], v[124:127]
	v_mfma_f32_16x16x32_bf16 v[120:123], v[150:153], v[180:183], v[120:123]
	v_mfma_f32_16x16x32_bf16 v[116:119], v[142:145], v[188:191], v[116:119]
	v_mfma_f32_16x16x32_bf16 v[112:115], v[150:153], v[188:191], v[112:115]
	v_mfma_f32_16x16x32_bf16 v[100:103], v[142:145], v[196:199], v[100:103]
	v_mfma_f32_16x16x32_bf16 v[96:99], v[150:153], v[196:199], v[96:99]
	v_mfma_f32_16x16x32_bf16 v[84:87], v[142:145], v[226:229], v[84:87]
	v_mfma_f32_16x16x32_bf16 v[80:83], v[150:153], v[226:229], v[80:83]
	v_mfma_f32_16x16x32_bf16 v[124:127], v[146:149], v[184:187], v[124:127]
	v_mfma_f32_16x16x32_bf16 v[120:123], v[154:157], v[184:187], v[120:123]
	v_mfma_f32_16x16x32_bf16 v[116:119], v[146:149], v[192:195], v[116:119]
	v_mfma_f32_16x16x32_bf16 v[112:115], v[154:157], v[192:195], v[112:115]
	v_mfma_f32_16x16x32_bf16 v[100:103], v[146:149], v[222:225], v[100:103]
	v_mfma_f32_16x16x32_bf16 v[96:99], v[154:157], v[222:225], v[96:99]
	v_mfma_f32_16x16x32_bf16 v[84:87], v[146:149], v[230:233], v[84:87]
	v_mfma_f32_16x16x32_bf16 v[80:83], v[154:157], v[230:233], v[80:83]
	s_setprio 0
	s_setprio 1
	v_mfma_f32_16x16x32_bf16 v[108:111], v[164:167], v[180:183], v[108:111]
	v_mfma_f32_16x16x32_bf16 v[104:107], v[172:175], v[180:183], v[104:107]
	v_mfma_f32_16x16x32_bf16 v[92:95], v[164:167], v[188:191], v[92:95]
	v_mfma_f32_16x16x32_bf16 v[88:91], v[172:175], v[188:191], v[88:91]
	v_mfma_f32_16x16x32_bf16 v[76:79], v[164:167], v[196:199], v[76:79]
	v_mfma_f32_16x16x32_bf16 v[72:75], v[172:175], v[196:199], v[72:75]
	v_mfma_f32_16x16x32_bf16 v[68:71], v[164:167], v[226:229], v[68:71]
	v_mfma_f32_16x16x32_bf16 v[64:67], v[172:175], v[226:229], v[64:67]
	v_mfma_f32_16x16x32_bf16 v[108:111], v[168:171], v[184:187], v[108:111]
	v_mfma_f32_16x16x32_bf16 v[104:107], v[176:179], v[184:187], v[104:107]
	v_mfma_f32_16x16x32_bf16 v[92:95], v[168:171], v[192:195], v[92:95]
	v_mfma_f32_16x16x32_bf16 v[88:91], v[176:179], v[192:195], v[88:91]
	v_mfma_f32_16x16x32_bf16 v[76:79], v[168:171], v[222:225], v[76:79]
	v_mfma_f32_16x16x32_bf16 v[72:75], v[176:179], v[222:225], v[72:75]
	v_mfma_f32_16x16x32_bf16 v[68:71], v[168:171], v[230:233], v[68:71]
	v_mfma_f32_16x16x32_bf16 v[64:67], v[176:179], v[230:233], v[64:67]
	s_setprio 0
	s_barrier
	s_add_i32 s56, s72, s24
	s_mov_b32 m0, s56
	ds_read_b128 v[180:183], v141 offset:49152
	ds_read_b128 v[184:187], v141 offset:50176
	ds_read_b128 v[188:191], v141 offset:51200
	ds_read_b128 v[192:195], v141 offset:52224
	ds_read_b128 v[196:199], v141 offset:53248
	ds_read_b128 v[222:225], v141 offset:54272
	ds_read_b128 v[226:229], v141 offset:55296
	ds_read_b128 v[230:233], v141 offset:56320
	s_add_u32 s52, s52, 0x80
	s_addc_u32 s53, s53, 0
	global_load_lds_dwordx4 v160, s[52:53]
	s_add_i32 m0, s56, 0x2000
	s_add_i32 s56, s73, s24
	global_load_lds_dwordx4 v128, s[52:53]
	s_add_u32 s52, s52, 0x160000
	s_addc_u32 s53, s53, 0
	s_mov_b32 m0, s56
	s_nop 0
	global_load_lds_dwordx4 v160, s[52:53]
	s_add_i32 m0, s56, 0x2000
	s_nop 0
	global_load_lds_dwordx4 v128, s[52:53]
	s_mov_b32 m0, s74
	s_nop 0
	global_load_lds_dwordx4 v132, s[98:99]
	s_mov_b32 m0, s75
	s_nop 0
	global_load_lds_dwordx4 v130, s[98:99]
	s_waitcnt vmcnt(8)
	s_waitcnt lgkmcnt(0)
	s_barrier
	s_setprio 1
	s_waitcnt lgkmcnt(0)
	v_mfma_f32_16x16x32_bf16 v[60:63], v[142:145], v[180:183], v[60:63]
	v_mfma_f32_16x16x32_bf16 v[56:59], v[150:153], v[180:183], v[56:59]
	v_mfma_f32_16x16x32_bf16 v[52:55], v[142:145], v[188:191], v[52:55]
	v_mfma_f32_16x16x32_bf16 v[48:51], v[150:153], v[188:191], v[48:51]
	v_mfma_f32_16x16x32_bf16 v[36:39], v[142:145], v[196:199], v[36:39]
	v_mfma_f32_16x16x32_bf16 v[32:35], v[150:153], v[196:199], v[32:35]
	v_mfma_f32_16x16x32_bf16 v[20:23], v[142:145], v[226:229], v[20:23]
	v_mfma_f32_16x16x32_bf16 v[16:19], v[150:153], v[226:229], v[16:19]
	v_mfma_f32_16x16x32_bf16 v[60:63], v[146:149], v[184:187], v[60:63]
	v_mfma_f32_16x16x32_bf16 v[56:59], v[154:157], v[184:187], v[56:59]
	v_mfma_f32_16x16x32_bf16 v[52:55], v[146:149], v[192:195], v[52:55]
	v_mfma_f32_16x16x32_bf16 v[48:51], v[154:157], v[192:195], v[48:51]
	v_mfma_f32_16x16x32_bf16 v[36:39], v[146:149], v[222:225], v[36:39]
	v_mfma_f32_16x16x32_bf16 v[32:35], v[154:157], v[222:225], v[32:35]
	v_mfma_f32_16x16x32_bf16 v[20:23], v[146:149], v[230:233], v[20:23]
	v_mfma_f32_16x16x32_bf16 v[16:19], v[154:157], v[230:233], v[16:19]
	s_setprio 0
	s_setprio 1
	v_mfma_f32_16x16x32_bf16 v[44:47], v[164:167], v[180:183], v[44:47]
	v_mfma_f32_16x16x32_bf16 v[40:43], v[172:175], v[180:183], v[40:43]
	v_mfma_f32_16x16x32_bf16 v[28:31], v[164:167], v[188:191], v[28:31]
	v_mfma_f32_16x16x32_bf16 v[24:27], v[172:175], v[188:191], v[24:27]
	v_mfma_f32_16x16x32_bf16 v[12:15], v[164:167], v[196:199], v[12:15]
	v_mfma_f32_16x16x32_bf16 v[8:11], v[172:175], v[196:199], v[8:11]
	v_mfma_f32_16x16x32_bf16 v[4:7], v[164:167], v[226:229], v[4:7]
	v_mfma_f32_16x16x32_bf16 v[0:3], v[172:175], v[226:229], v[0:3]
	v_mfma_f32_16x16x32_bf16 v[44:47], v[168:171], v[184:187], v[44:47]
	v_mfma_f32_16x16x32_bf16 v[40:43], v[176:179], v[184:187], v[40:43]
	v_mfma_f32_16x16x32_bf16 v[28:31], v[168:171], v[192:195], v[28:31]
	v_mfma_f32_16x16x32_bf16 v[24:27], v[176:179], v[192:195], v[24:27]
	v_mfma_f32_16x16x32_bf16 v[12:15], v[168:171], v[222:225], v[12:15]
	v_mfma_f32_16x16x32_bf16 v[8:11], v[176:179], v[222:225], v[8:11]
	v_mfma_f32_16x16x32_bf16 v[4:7], v[168:171], v[230:233], v[4:7]
	v_mfma_f32_16x16x32_bf16 v[0:3], v[176:179], v[230:233], v[0:3]
	s_setprio 0
	s_barrier
	s_add_i32 s83, s83, 2
	s_add_u32 s81, s81, 0x100
	s_addc_u32 s82, s82, 0
	s_cmpk_gt_u32 s83, 0x55
	s_mov_b64 s[72:73], s[4:5]
	s_cbranch_scc0 .LBB0_52
	s_and_b64 vcc, exec, s[42:43]
	s_cbranch_vccz .LBB0_55
	s_barrier

; #define PG8_STAGE(bufoff, gbase, voff) do { _Pragma("unroll") for (int _i = 0; _i < 2; ++_i) \
;         __builtin_amdgcn_global_load_lds((const unsigned*)((const char*)(gbase) + (voff)[_i]), (PG8_LAS unsigned*)(lds + (bufoff) + ldsw + _i * 8192), 16, 0, 0); } while (0)
; #define PG8_LDA(dst, b, h) do { _Pragma("unroll") for (int m = 0; m < 4; ++m) _Pragma("unroll") for (int k = 0; k < 2; ++k) dst[m][k] = *(const PG8_LAS bf16x8*)(lds + PG8_SA(b, h) + aoff + m * 2048 + k * 1024); } while (0)
; #define PG8_LDB(dst, b, h) do { _Pragma("unroll") for (int n = 0; n < 2; ++n) _Pragma("unroll") for (int k = 0; k < 2; ++k) dst[n][k] = *(const PG8_LAS bf16x8*)(lds + PG8_SB(b, h) + boff + n * 2048 + k * 1024); } while (0)
; #define PG8_MMA(ai, bj, At, Bt) do { __builtin_amdgcn_s_setprio(1); _Pragma("unroll") for (int m = 0; m < 4; ++m) _Pragma("unroll") for (int n = 0; n < 2; ++n) _Pragma("unroll") for (int k = 0; k < 2; ++k) \
;         acc[ai][bj][m][n] = __builtin_amdgcn_mfma_f32_16x16x32_bf16(Bt[n][k], At[m][k], acc[ai][bj][m][n], 0, 0, 0); __builtin_amdgcn_s_setprio(0); } while (0)
; #define PG8_WAIT_V(n) asm volatile("s_waitcnt vmcnt(" #n ")" ::: "memory")
; #define PG8_WAIT_L(n) asm volatile("s_waitcnt lgkmcnt(" #n ")" ::: "memory")
; template <class Epi, class Sched, bool ALIGN_EPI = false, bool SP2 = false>
; __device__ __forceinline__ void gemm_phase(PG8_LAS unsigned char* lds, const Gemm g, const Sched& S, const Epi& E) {
;     ...
;             const bool last = (t == nt - 2);
;             const char* a1 = cA + (size_t)(t + 1) * kstep;
;             const char* a2 = last ? nA : cA + (size_t)(t + 2) * kstep; const char* b2 = last ? nB : cB + (size_t)(t + 2) * kstep;
;             const char* a3 = a2 + kstep; const char* b3 = b2 + kstep;
;             if (last && has_next) S.a_ready(nxt);
;             if constexpr (SP2) {
;             PG8_LDB(B0, 0, 0); PG8_LDB(B1, 0, 1); PG8_SCHED; PG8_LDA(At, 0, 0); PG8_STAGE(PG8_SA(1, 1), a1 + hstep, voffA);
;             PG8_WAIT_V(8); PG8_WAIT_L(0); PG8_BAR; PG8_MMA(0, 0, At, B0); PG8_MMA(0, 1, At, B1); PG8_BAR; PG8_SCHED;
;             PG8_LDA(At, 0, 1); PG8_STAGE(PG8_SB(0, 0), b2, voffB); PG8_STAGE(PG8_SB(0, 1), b2 + hstep, voffB); PG8_STAGE(PG8_SA(0, 0), a2, voffA);
;             PG8_WAIT_V(8); PG8_WAIT_L(0); PG8_BAR; PG8_MMA(1, 0, At, B0); PG8_MMA(1, 1, At, B1); PG8_BAR; PG8_SCHED;
.LBB0_86:
	s_add_u32 s4, s82, 0xfffc0080
	s_addc_u32 s5, s83, -1
	s_add_i32 s88, 0, 0x10000
	s_cmp_eq_u32 s87, 12
	s_cselect_b32 s53, s7, s5
	s_cselect_b32 s52, s15, s4
	v_add_u32_e32 v144, s88, v147
	s_cselect_b32 s5, s24, s43
	s_cselect_b32 s4, s28, s29
	s_add_i32 s90, 0, 0x14000
	ds_read_b128 v[140:143], v144
	ds_read_b128 v[150:153], v144 offset:1024
	ds_read_b128 v[154:157], v144 offset:2048
	ds_read_b128 v[164:167], v144 offset:3072
	v_add_u32_e32 v144, s90, v147
	ds_read_b128 v[168:171], v144
	ds_read_b128 v[172:175], v144 offset:1024
	ds_read_b128 v[176:179], v144 offset:2048
	ds_read_b128 v[180:183], v144 offset:3072
	s_add_i32 m0, s63, 0xc000
	ds_read_b128 v[184:187], v149
	ds_read_b128 v[188:191], v149 offset:1024
	ds_read_b128 v[192:195], v149 offset:2048
	ds_read_b128 v[196:199], v149 offset:3072
	ds_read_b128 v[222:225], v149 offset:4096
	ds_read_b128 v[226:229], v149 offset:5120
	ds_read_b128 v[230:233], v149 offset:6144
	ds_read_b128 v[234:237], v149 offset:7168
	global_load_lds_dwordx4 v136, s[82:83]
	s_add_i32 m0, s63, 0xe000
	s_nop 0
	global_load_lds_dwordx4 v138, s[82:83]
	s_waitcnt vmcnt(8)
	s_waitcnt lgkmcnt(0)
	s_barrier
	s_setprio 1
	s_waitcnt lgkmcnt(0)
	v_mfma_f32_16x16x32_bf16 v[124:127], v[140:143], v[184:187], v[124:127]
	v_mfma_f32_16x16x32_bf16 v[120:123], v[154:157], v[184:187], v[120:123]
	v_mfma_f32_16x16x32_bf16 v[108:111], v[140:143], v[192:195], v[108:111]
	v_mfma_f32_16x16x32_bf16 v[104:107], v[154:157], v[192:195], v[104:107]
	v_mfma_f32_16x16x32_bf16 v[92:95], v[140:143], v[222:225], v[92:95]
	v_mfma_f32_16x16x32_bf16 v[88:91], v[154:157], v[222:225], v[88:91]
	v_mfma_f32_16x16x32_bf16 v[76:79], v[140:143], v[230:233], v[76:79]
	v_mfma_f32_16x16x32_bf16 v[72:75], v[154:157], v[230:233], v[72:75]
	v_mfma_f32_16x16x32_bf16 v[124:127], v[150:153], v[188:191], v[124:127]
	v_mfma_f32_16x16x32_bf16 v[120:123], v[164:167], v[188:191], v[120:123]
	v_mfma_f32_16x16x32_bf16 v[108:111], v[150:153], v[196:199], v[108:111]
	v_mfma_f32_16x16x32_bf16 v[104:107], v[164:167], v[196:199], v[104:107]
	v_mfma_f32_16x16x32_bf16 v[92:95], v[150:153], v[226:229], v[92:95]
	v_mfma_f32_16x16x32_bf16 v[88:91], v[164:167], v[226:229], v[88:91]
	v_mfma_f32_16x16x32_bf16 v[76:79], v[150:153], v[234:237], v[76:79]
	v_mfma_f32_16x16x32_bf16 v[72:75], v[164:167], v[234:237], v[72:75]
	s_setprio 0
	s_setprio 1
	v_mfma_f32_16x16x32_bf16 v[116:119], v[168:171], v[184:187], v[116:119]
	v_mfma_f32_16x16x32_bf16 v[112:115], v[176:179], v[184:187], v[112:115]
	v_mfma_f32_16x16x32_bf16 v[100:103], v[168:171], v[192:195], v[100:103]
	v_mfma_f32_16x16x32_bf16 v[96:99], v[176:179], v[192:195], v[96:99]
	v_mfma_f32_16x16x32_bf16 v[84:87], v[168:171], v[222:225], v[84:87]
	v_mfma_f32_16x16x32_bf16 v[80:83], v[176:179], v[222:225], v[80:83]
	v_mfma_f32_16x16x32_bf16 v[68:71], v[168:171], v[230:233], v[68:71]
	v_mfma_f32_16x16x32_bf16 v[64:67], v[176:179], v[230:233], v[64:67]
	v_mfma_f32_16x16x32_bf16 v[116:119], v[172:175], v[188:191], v[116:119]
	v_mfma_f32_16x16x32_bf16 v[112:115], v[180:183], v[188:191], v[112:115]
	v_mfma_f32_16x16x32_bf16 v[100:103], v[172:175], v[196:199], v[100:103]
	v_mfma_f32_16x16x32_bf16 v[96:99], v[180:183], v[196:199], v[96:99]
	v_mfma_f32_16x16x32_bf16 v[84:87], v[172:175], v[226:229], v[84:87]
	v_mfma_f32_16x16x32_bf16 v[80:83], v[180:183], v[226:229], v[80:83]
	v_mfma_f32_16x16x32_bf16 v[68:71], v[172:175], v[234:237], v[68:71]
	v_mfma_f32_16x16x32_bf16 v[64:67], v[180:183], v[234:237], v[64:67]
	s_setprio 0
	s_barrier
	s_add_i32 s88, s88, s59
	s_mov_b32 m0, s88
	ds_read_b128 v[184:187], v149 offset:16384
	ds_read_b128 v[188:191], v149 offset:17408
	ds_read_b128 v[192:195], v149 offset:18432
	ds_read_b128 v[196:199], v149 offset:19456
	ds_read_b128 v[222:225], v149 offset:20480
	ds_read_b128 v[226:229], v149 offset:21504
	ds_read_b128 v[230:233], v149 offset:22528
	ds_read_b128 v[234:237], v149 offset:23552
	global_load_lds_dwordx4 v130, s[4:5]
	s_add_i32 m0, s88, 0x2000
	s_add_u32 s88, s4, 0x40000
	s_addc_u32 s89, s5, 0
	s_add_i32 s90, s90, s59
	global_load_lds_dwordx4 v134, s[4:5]
	s_mov_b32 m0, s90
	s_nop 0
	global_load_lds_dwordx4 v130, s[88:89]
	s_add_i32 m0, s90, 0x2000
	s_nop 0
	global_load_lds_dwordx4 v134, s[88:89]
	s_mov_b32 m0, s63
	s_nop 0
	global_load_lds_dwordx4 v128, s[52:53]
	s_mov_b32 m0, s74
	s_nop 0
	global_load_lds_dwordx4 v132, s[52:53]
	s_add_u32 s98, s52, 0x80
	s_addc_u32 s99, s53, 0
	s_waitcnt vmcnt(8)
	s_waitcnt lgkmcnt(0)
	s_barrier
	s_setprio 1
	s_waitcnt lgkmcnt(0)
	v_mfma_f32_16x16x32_bf16 v[60:63], v[140:143], v[184:187], v[60:63]
	v_mfma_f32_16x16x32_bf16 v[56:59], v[154:157], v[184:187], v[56:59]
	v_mfma_f32_16x16x32_bf16 v[44:47], v[140:143], v[192:195], v[44:47]
	v_mfma_f32_16x16x32_bf16 v[40:43], v[154:157], v[192:195], v[40:43]
	v_mfma_f32_16x16x32_bf16 v[28:31], v[140:143], v[222:225], v[28:31]
	v_mfma_f32_16x16x32_bf16 v[24:27], v[154:157], v[222:225], v[24:27]
	v_mfma_f32_16x16x32_bf16 v[12:15], v[140:143], v[230:233], v[12:15]
	v_mfma_f32_16x16x32_bf16 v[8:11], v[154:157], v[230:233], v[8:11]
	v_mfma_f32_16x16x32_bf16 v[60:63], v[150:153], v[188:191], v[60:63]
	v_mfma_f32_16x16x32_bf16 v[56:59], v[164:167], v[188:191], v[56:59]
	v_mfma_f32_16x16x32_bf16 v[44:47], v[150:153], v[196:199], v[44:47]
	v_mfma_f32_16x16x32_bf16 v[40:43], v[164:167], v[196:199], v[40:43]
	v_mfma_f32_16x16x32_bf16 v[28:31], v[150:153], v[226:229], v[28:31]
	v_mfma_f32_16x16x32_bf16 v[24:27], v[164:167], v[226:229], v[24:27]
	v_mfma_f32_16x16x32_bf16 v[12:15], v[150:153], v[234:237], v[12:15]
	v_mfma_f32_16x16x32_bf16 v[8:11], v[164:167], v[234:237], v[8:11]
	s_setprio 0
	s_setprio 1
	v_mfma_f32_16x16x32_bf16 v[52:55], v[168:171], v[184:187], v[52:55]
	v_mfma_f32_16x16x32_bf16 v[48:51], v[176:179], v[184:187], v[48:51]
	v_mfma_f32_16x16x32_bf16 v[36:39], v[168:171], v[192:195], v[36:39]
	v_mfma_f32_16x16x32_bf16 v[32:35], v[176:179], v[192:195], v[32:35]
	v_mfma_f32_16x16x32_bf16 v[20:23], v[168:171], v[222:225], v[20:23]
	v_mfma_f32_16x16x32_bf16 v[16:19], v[176:179], v[222:225], v[16:19]
	v_mfma_f32_16x16x32_bf16 v[4:7], v[168:171], v[230:233], v[4:7]
	v_mfma_f32_16x16x32_bf16 v[0:3], v[176:179], v[230:233], v[0:3]
	v_mfma_f32_16x16x32_bf16 v[52:55], v[172:175], v[188:191], v[52:55]
	v_mfma_f32_16x16x32_bf16 v[48:51], v[180:183], v[188:191], v[48:51]
	v_mfma_f32_16x16x32_bf16 v[36:39], v[172:175], v[196:199], v[36:39]
	v_mfma_f32_16x16x32_bf16 v[32:35], v[180:183], v[196:199], v[32:35]
	v_mfma_f32_16x16x32_bf16 v[20:23], v[172:175], v[226:229], v[20:23]
	v_mfma_f32_16x16x32_bf16 v[16:19], v[180:183], v[226:229], v[16:19]
	v_mfma_f32_16x16x32_bf16 v[4:7], v[172:175], v[234:237], v[4:7]
	v_mfma_f32_16x16x32_bf16 v[0:3], v[180:183], v[234:237], v[0:3]
	s_setprio 0
	s_barrier
; #define PG8_STAGE(bufoff, gbase, voff) do { _Pragma("unroll") for (int _i = 0; _i < 2; ++_i) \
;         __builtin_amdgcn_global_load_lds((const unsigned*)((const char*)(gbase) + (voff)[_i]), (PG8_LAS unsigned*)(lds + (bufoff) + ldsw + _i * 8192), 16, 0, 0); } while (0)
; #define PG8_LDA(dst, b, h) do { _Pragma("unroll") for (int m = 0; m < 4; ++m) _Pragma("unroll") for (int k = 0; k < 2; ++k) dst[m][k] = *(const PG8_LAS bf16x8*)(lds + PG8_SA(b, h) + aoff + m * 2048 + k * 1024); } while (0)
; #define PG8_LDB(dst, b, h) do { _Pragma("unroll") for (int n = 0; n < 2; ++n) _Pragma("unroll") for (int k = 0; k < 2; ++k) dst[n][k] = *(const PG8_LAS bf16x8*)(lds + PG8_SB(b, h) + boff + n * 2048 + k * 1024); } while (0)
; #define PG8_MMA(ai, bj, At, Bt) do { __builtin_amdgcn_s_setprio(1); _Pragma("unroll") for (int m = 0; m < 4; ++m) _Pragma("unroll") for (int n = 0; n < 2; ++n) _Pragma("unroll") for (int k = 0; k < 2; ++k) \
;         acc[ai][bj][m][n] = __builtin_amdgcn_mfma_f32_16x16x32_bf16(Bt[n][k], At[m][k], acc[ai][bj][m][n], 0, 0, 0); __builtin_amdgcn_s_setprio(0); } while (0)
; #define PG8_WAIT_V(n) asm volatile("s_waitcnt vmcnt(" #n ")" ::: "memory")
; #define PG8_WAIT_L(n) asm volatile("s_waitcnt lgkmcnt(" #n ")" ::: "memory")
; #define PG8_BAR __builtin_amdgcn_s_barrier()
; #define PG8_SCHED __builtin_amdgcn_sched_barrier(0)
; template <class Epi, class Sched, bool ALIGN_EPI = false, bool SP2 = false>
; __device__ __forceinline__ void gemm_phase(PG8_LAS unsigned char* lds, const Gemm g, const Sched& S, const Epi& E) {
;     ...
;             PG8_LDB(B0, 1, 0); PG8_LDB(B1, 1, 1); PG8_SCHED; PG8_LDA(At, 1, 0); PG8_STAGE(PG8_SA(0, 1), a2 + hstep, voffA);
;             PG8_WAIT_V(8); PG8_WAIT_L(0); PG8_BAR; PG8_MMA(0, 0, At, B0); PG8_MMA(0, 1, At, B1); PG8_BAR; PG8_SCHED;
;             PG8_LDA(At, 1, 1); PG8_STAGE(PG8_SB(1, 0), b3, voffB); PG8_STAGE(PG8_SB(1, 1), b3 + hstep, voffB); PG8_STAGE(PG8_SA(1, 0), a3, voffA);
;             PG8_WAIT_V(8); PG8_WAIT_L(0); PG8_BAR; PG8_MMA(1, 0, At, B0); PG8_MMA(1, 1, At, B1); PG8_BAR; PG8_SCHED;
	s_add_i32 s88, 0, 0x18000
	v_add_u32_e32 v160, s88, v147
	s_add_i32 s89, 0, 0x1c000
	ds_read_b128 v[140:143], v160
	ds_read_b128 v[150:153], v160 offset:1024
	ds_read_b128 v[154:157], v160 offset:2048
	ds_read_b128 v[164:167], v160 offset:3072
	v_add_u32_e32 v160, s89, v147
	ds_read_b128 v[168:171], v160
	ds_read_b128 v[172:175], v160 offset:1024
	ds_read_b128 v[176:179], v160 offset:2048
	ds_read_b128 v[180:183], v160 offset:3072
	s_add_u32 s52, s52, 0x40000
	s_addc_u32 s53, s53, 0
	s_mov_b32 m0, s75
	ds_read_b128 v[184:187], v149 offset:32768
	ds_read_b128 v[188:191], v149 offset:33792
	ds_read_b128 v[192:195], v149 offset:34816
	ds_read_b128 v[196:199], v149 offset:35840
	ds_read_b128 v[222:225], v149 offset:36864
	ds_read_b128 v[226:229], v149 offset:37888
	ds_read_b128 v[230:233], v149 offset:38912
	ds_read_b128 v[234:237], v149 offset:39936
	global_load_lds_dwordx4 v128, s[52:53]
	s_mov_b32 m0, s81
	s_nop 0
	global_load_lds_dwordx4 v132, s[52:53]
	s_waitcnt vmcnt(8)
	s_waitcnt lgkmcnt(0)
	s_barrier
	s_setprio 1
	s_waitcnt lgkmcnt(0)
	v_mfma_f32_16x16x32_bf16 v[124:127], v[140:143], v[184:187], v[124:127]
	v_mfma_f32_16x16x32_bf16 v[120:123], v[154:157], v[184:187], v[120:123]
	v_mfma_f32_16x16x32_bf16 v[108:111], v[140:143], v[192:195], v[108:111]
	v_mfma_f32_16x16x32_bf16 v[104:107], v[154:157], v[192:195], v[104:107]
	v_mfma_f32_16x16x32_bf16 v[92:95], v[140:143], v[222:225], v[92:95]
	v_mfma_f32_16x16x32_bf16 v[88:91], v[154:157], v[222:225], v[88:91]
	v_mfma_f32_16x16x32_bf16 v[76:79], v[140:143], v[230:233], v[76:79]
	v_mfma_f32_16x16x32_bf16 v[72:75], v[154:157], v[230:233], v[72:75]
	v_mfma_f32_16x16x32_bf16 v[124:127], v[150:153], v[188:191], v[124:127]
	v_mfma_f32_16x16x32_bf16 v[120:123], v[164:167], v[188:191], v[120:123]
	v_mfma_f32_16x16x32_bf16 v[108:111], v[150:153], v[196:199], v[108:111]
	v_mfma_f32_16x16x32_bf16 v[104:107], v[164:167], v[196:199], v[104:107]
	v_mfma_f32_16x16x32_bf16 v[92:95], v[150:153], v[226:229], v[92:95]
	v_mfma_f32_16x16x32_bf16 v[88:91], v[164:167], v[226:229], v[88:91]
	v_mfma_f32_16x16x32_bf16 v[76:79], v[150:153], v[234:237], v[76:79]
	v_mfma_f32_16x16x32_bf16 v[72:75], v[164:167], v[234:237], v[72:75]
	s_setprio 0
	s_setprio 1
	v_mfma_f32_16x16x32_bf16 v[116:119], v[168:171], v[184:187], v[116:119]
	v_mfma_f32_16x16x32_bf16 v[112:115], v[176:179], v[184:187], v[112:115]
	v_mfma_f32_16x16x32_bf16 v[100:103], v[168:171], v[192:195], v[100:103]
	v_mfma_f32_16x16x32_bf16 v[96:99], v[176:179], v[192:195], v[96:99]
	v_mfma_f32_16x16x32_bf16 v[84:87], v[168:171], v[222:225], v[84:87]
	v_mfma_f32_16x16x32_bf16 v[80:83], v[176:179], v[222:225], v[80:83]
	v_mfma_f32_16x16x32_bf16 v[68:71], v[168:171], v[230:233], v[68:71]
	v_mfma_f32_16x16x32_bf16 v[64:67], v[176:179], v[230:233], v[64:67]
	v_mfma_f32_16x16x32_bf16 v[116:119], v[172:175], v[188:191], v[116:119]
	v_mfma_f32_16x16x32_bf16 v[112:115], v[180:183], v[188:191], v[112:115]
	v_mfma_f32_16x16x32_bf16 v[100:103], v[172:175], v[196:199], v[100:103]
	v_mfma_f32_16x16x32_bf16 v[96:99], v[180:183], v[196:199], v[96:99]
	v_mfma_f32_16x16x32_bf16 v[84:87], v[172:175], v[226:229], v[84:87]
	v_mfma_f32_16x16x32_bf16 v[80:83], v[180:183], v[226:229], v[80:83]
	v_mfma_f32_16x16x32_bf16 v[68:71], v[172:175], v[234:237], v[68:71]
	v_mfma_f32_16x16x32_bf16 v[64:67], v[180:183], v[234:237], v[64:67]
	s_setprio 0
	s_barrier
	s_add_i32 s52, s88, s59
	s_mov_b32 m0, s52
	ds_read_b128 v[184:187], v149 offset:49152
	ds_read_b128 v[188:191], v149 offset:50176
	ds_read_b128 v[192:195], v149 offset:51200
	ds_read_b128 v[196:199], v149 offset:52224
	ds_read_b128 v[222:225], v149 offset:53248
	ds_read_b128 v[226:229], v149 offset:54272
	ds_read_b128 v[230:233], v149 offset:55296
	ds_read_b128 v[234:237], v149 offset:56320
	s_add_u32 s4, s4, 0x80
	s_addc_u32 s5, s5, 0
	global_load_lds_dwordx4 v130, s[4:5]
	s_add_i32 m0, s52, 0x2000
	s_add_i32 s52, s89, s59
	global_load_lds_dwordx4 v134, s[4:5]
	s_add_u32 s4, s4, 0x40000
	s_addc_u32 s5, s5, 0
	s_mov_b32 m0, s52
	s_nop 0
	global_load_lds_dwordx4 v130, s[4:5]
	s_add_i32 m0, s52, 0x2000
	s_nop 0
	global_load_lds_dwordx4 v134, s[4:5]
	s_mov_b32 m0, s84
	s_nop 0
	global_load_lds_dwordx4 v128, s[98:99]
	s_mov_b32 m0, s85
	s_nop 0
	global_load_lds_dwordx4 v132, s[98:99]
	s_waitcnt vmcnt(8)
	s_waitcnt lgkmcnt(0)
	s_barrier
	s_setprio 1
	s_waitcnt lgkmcnt(0)
	v_mfma_f32_16x16x32_bf16 v[60:63], v[140:143], v[184:187], v[60:63]
	v_mfma_f32_16x16x32_bf16 v[56:59], v[154:157], v[184:187], v[56:59]
	v_mfma_f32_16x16x32_bf16 v[44:47], v[140:143], v[192:195], v[44:47]
	v_mfma_f32_16x16x32_bf16 v[40:43], v[154:157], v[192:195], v[40:43]
	v_mfma_f32_16x16x32_bf16 v[28:31], v[140:143], v[222:225], v[28:31]
	v_mfma_f32_16x16x32_bf16 v[24:27], v[154:157], v[222:225], v[24:27]
	v_mfma_f32_16x16x32_bf16 v[12:15], v[140:143], v[230:233], v[12:15]
	v_mfma_f32_16x16x32_bf16 v[8:11], v[154:157], v[230:233], v[8:11]
	v_mfma_f32_16x16x32_bf16 v[60:63], v[150:153], v[188:191], v[60:63]
	v_mfma_f32_16x16x32_bf16 v[56:59], v[164:167], v[188:191], v[56:59]
	v_mfma_f32_16x16x32_bf16 v[44:47], v[150:153], v[196:199], v[44:47]
	v_mfma_f32_16x16x32_bf16 v[40:43], v[164:167], v[196:199], v[40:43]
	v_mfma_f32_16x16x32_bf16 v[28:31], v[150:153], v[226:229], v[28:31]
	v_mfma_f32_16x16x32_bf16 v[24:27], v[164:167], v[226:229], v[24:27]
	v_mfma_f32_16x16x32_bf16 v[12:15], v[150:153], v[234:237], v[12:15]
	v_mfma_f32_16x16x32_bf16 v[8:11], v[164:167], v[234:237], v[8:11]
	s_setprio 0
	s_setprio 1
	v_mfma_f32_16x16x32_bf16 v[52:55], v[168:171], v[184:187], v[52:55]
	v_mfma_f32_16x16x32_bf16 v[48:51], v[176:179], v[184:187], v[48:51]
	v_mfma_f32_16x16x32_bf16 v[36:39], v[168:171], v[192:195], v[36:39]
	v_mfma_f32_16x16x32_bf16 v[32:35], v[176:179], v[192:195], v[32:35]
	v_mfma_f32_16x16x32_bf16 v[20:23], v[168:171], v[222:225], v[20:23]
	v_mfma_f32_16x16x32_bf16 v[16:19], v[176:179], v[222:225], v[16:19]
	v_mfma_f32_16x16x32_bf16 v[4:7], v[168:171], v[230:233], v[4:7]
	v_mfma_f32_16x16x32_bf16 v[0:3], v[176:179], v[230:233], v[0:3]
	v_mfma_f32_16x16x32_bf16 v[52:55], v[172:175], v[188:191], v[52:55]
	v_mfma_f32_16x16x32_bf16 v[48:51], v[180:183], v[188:191], v[48:51]
	v_mfma_f32_16x16x32_bf16 v[36:39], v[172:175], v[196:199], v[36:39]
	v_mfma_f32_16x16x32_bf16 v[32:35], v[180:183], v[196:199], v[32:35]
	v_mfma_f32_16x16x32_bf16 v[20:23], v[172:175], v[226:229], v[20:23]
	v_mfma_f32_16x16x32_bf16 v[16:19], v[180:183], v[226:229], v[16:19]
	v_mfma_f32_16x16x32_bf16 v[4:7], v[172:175], v[234:237], v[4:7]
	v_mfma_f32_16x16x32_bf16 v[0:3], v[180:183], v[234:237], v[0:3]
	s_setprio 0
	s_barrier
	s_add_i32 s87, s87, 2
	s_add_u32 s82, s82, 0x100
	s_addc_u32 s83, s83, 0
	s_add_u32 s29, s29, 0x100
	s_addc_u32 s43, s43, 0
	s_cmp_gt_u32 s87, 13
	s_cbranch_scc0 .LBB0_86
	s_and_b64 vcc, exec, s[12:13]
	s_cbranch_vccz .LBB0_89
	s_barrier

; #define PG8_STAGE(bufoff, gbase, voff) do { _Pragma("unroll") for (int _i = 0; _i < 2; ++_i) \
;         __builtin_amdgcn_global_load_lds((const unsigned*)((const char*)(gbase) + (voff)[_i]), (PG8_LAS unsigned*)(lds + (bufoff) + ldsw + _i * 8192), 16, 0, 0); } while (0)
; #define PG8_LDA(dst, b, h) do { _Pragma("unroll") for (int m = 0; m < 4; ++m) _Pragma("unroll") for (int k = 0; k < 2; ++k) dst[m][k] = *(const PG8_LAS bf16x8*)(lds + PG8_SA(b, h) + aoff + m * 2048 + k * 1024); } while (0)
; #define PG8_LDB(dst, b, h) do { _Pragma("unroll") for (int n = 0; n < 2; ++n) _Pragma("unroll") for (int k = 0; k < 2; ++k) dst[n][k] = *(const PG8_LAS bf16x8*)(lds + PG8_SB(b, h) + boff + n * 2048 + k * 1024); } while (0)
; #define PG8_MMA(ai, bj, At, Bt) do { __builtin_amdgcn_s_setprio(1); _Pragma("unroll") for (int m = 0; m < 4; ++m) _Pragma("unroll") for (int n = 0; n < 2; ++n) _Pragma("unroll") for (int k = 0; k < 2; ++k) \
;         acc[ai][bj][m][n] = __builtin_amdgcn_mfma_f32_16x16x32_bf16(Bt[n][k], At[m][k], acc[ai][bj][m][n], 0, 0, 0); __builtin_amdgcn_s_setprio(0); } while (0)
; #define PG8_WAIT_V(n) asm volatile("s_waitcnt vmcnt(" #n ")" ::: "memory")
; #define PG8_WAIT_L(n) asm volatile("s_waitcnt lgkmcnt(" #n ")" ::: "memory")
; template <class Epi, class Sched, bool ALIGN_EPI = false, bool SP2 = false>
; __device__ __forceinline__ void gemm_phase(PG8_LAS unsigned char* lds, const Gemm g, const Sched& S, const Epi& E) {
;     ...
;             const bool last = (t == nt - 2);
;             const char* a1 = cA + (size_t)(t + 1) * kstep;
;             const char* a2 = last ? nA : cA + (size_t)(t + 2) * kstep; const char* b2 = last ? nB : cB + (size_t)(t + 2) * kstep;
;             const char* a3 = a2 + kstep; const char* b3 = b2 + kstep;
;             if (last && has_next) S.a_ready(nxt);
;             if constexpr (SP2) {
;             PG8_LDB(B0, 0, 0); PG8_LDB(B1, 0, 1); PG8_SCHED; PG8_LDA(At, 0, 0); PG8_STAGE(PG8_SA(1, 1), a1 + hstep, voffA);
;             PG8_WAIT_V(8); PG8_WAIT_L(0); PG8_BAR; PG8_MMA(0, 0, At, B0); PG8_MMA(0, 1, At, B1); PG8_BAR; PG8_SCHED;
;             PG8_LDA(At, 0, 1); PG8_STAGE(PG8_SB(0, 0), b2, voffB); PG8_STAGE(PG8_SB(0, 1), b2 + hstep, voffB); PG8_STAGE(PG8_SA(0, 0), a2, voffA);
;             PG8_WAIT_V(8); PG8_WAIT_L(0); PG8_BAR; PG8_MMA(1, 0, At, B0); PG8_MMA(1, 1, At, B1); PG8_BAR; PG8_SCHED;
.LBB0_322:
	s_add_u32 s4, s14, 0xfff80080
	s_addc_u32 s5, s15, -1
	s_add_i32 s56, 0, 0x10000
	s_cmp_eq_u32 s55, 28
	s_cselect_b32 s53, s1, s5
	s_cselect_b32 s52, s28, s4
	v_add_u32_e32 v158, s56, v139
	s_cselect_b32 s5, s29, s54
	s_cselect_b32 s4, s43, s45
	s_add_i32 vcc_lo, 0, 0x14000
	s_waitcnt lgkmcnt(0)
	ds_read_b128 v[154:157], v158
	ds_read_b128 v[164:167], v158 offset:1024
	ds_read_b128 v[168:171], v158 offset:2048
	ds_read_b128 v[172:175], v158 offset:3072
	v_add_u32_e32 v158, vcc_lo, v139
	ds_read_b128 v[176:179], v158
	ds_read_b128 v[180:183], v158 offset:1024
	ds_read_b128 v[184:187], v158 offset:2048
	ds_read_b128 v[188:191], v158 offset:3072
	s_add_i32 m0, s89, 0xc000
	ds_read_b128 v[192:195], v145
	ds_read_b128 v[196:199], v145 offset:1024
	ds_read_b128 v[222:225], v145 offset:2048
	ds_read_b128 v[226:229], v145 offset:3072
	ds_read_b128 v[230:233], v145 offset:4096
	ds_read_b128 v[234:237], v145 offset:5120
	ds_read_b128 v[238:241], v145 offset:6144
	ds_read_b128 v[242:245], v145 offset:7168
	global_load_lds_dwordx4 v150, s[14:15]
	s_add_i32 m0, s89, 0xe000
	s_nop 0
	global_load_lds_dwordx4 v152, s[14:15]
	s_waitcnt vmcnt(8)
	s_waitcnt lgkmcnt(0)
	s_barrier
	s_setprio 1
	s_waitcnt lgkmcnt(0)
	v_mfma_f32_16x16x32_bf16 v[124:127], v[154:157], v[192:195], v[124:127]
	v_mfma_f32_16x16x32_bf16 v[120:123], v[168:171], v[192:195], v[120:123]
	v_mfma_f32_16x16x32_bf16 v[116:119], v[154:157], v[222:225], v[116:119]
	v_mfma_f32_16x16x32_bf16 v[112:115], v[168:171], v[222:225], v[112:115]
	v_mfma_f32_16x16x32_bf16 v[108:111], v[154:157], v[230:233], v[108:111]
	v_mfma_f32_16x16x32_bf16 v[104:107], v[168:171], v[230:233], v[104:107]
	v_mfma_f32_16x16x32_bf16 v[100:103], v[154:157], v[238:241], v[100:103]
	v_mfma_f32_16x16x32_bf16 v[96:99], v[168:171], v[238:241], v[96:99]
	v_mfma_f32_16x16x32_bf16 v[124:127], v[164:167], v[196:199], v[124:127]
	v_mfma_f32_16x16x32_bf16 v[120:123], v[172:175], v[196:199], v[120:123]
	v_mfma_f32_16x16x32_bf16 v[116:119], v[164:167], v[226:229], v[116:119]
	v_mfma_f32_16x16x32_bf16 v[112:115], v[172:175], v[226:229], v[112:115]
	v_mfma_f32_16x16x32_bf16 v[108:111], v[164:167], v[234:237], v[108:111]
	v_mfma_f32_16x16x32_bf16 v[104:107], v[172:175], v[234:237], v[104:107]
	v_mfma_f32_16x16x32_bf16 v[100:103], v[164:167], v[242:245], v[100:103]
	v_mfma_f32_16x16x32_bf16 v[96:99], v[172:175], v[242:245], v[96:99]
	s_setprio 0
	s_setprio 1
	v_mfma_f32_16x16x32_bf16 v[92:95], v[176:179], v[192:195], v[92:95]
	v_mfma_f32_16x16x32_bf16 v[88:91], v[184:187], v[192:195], v[88:91]
	v_mfma_f32_16x16x32_bf16 v[84:87], v[176:179], v[222:225], v[84:87]
	v_mfma_f32_16x16x32_bf16 v[80:83], v[184:187], v[222:225], v[80:83]
	v_mfma_f32_16x16x32_bf16 v[76:79], v[176:179], v[230:233], v[76:79]
	v_mfma_f32_16x16x32_bf16 v[72:75], v[184:187], v[230:233], v[72:75]
	v_mfma_f32_16x16x32_bf16 v[68:71], v[176:179], v[238:241], v[68:71]
	v_mfma_f32_16x16x32_bf16 v[64:67], v[184:187], v[238:241], v[64:67]
	v_mfma_f32_16x16x32_bf16 v[92:95], v[180:183], v[196:199], v[92:95]
	v_mfma_f32_16x16x32_bf16 v[88:91], v[188:191], v[196:199], v[88:91]
	v_mfma_f32_16x16x32_bf16 v[84:87], v[180:183], v[226:229], v[84:87]
	v_mfma_f32_16x16x32_bf16 v[80:83], v[188:191], v[226:229], v[80:83]
	v_mfma_f32_16x16x32_bf16 v[76:79], v[180:183], v[234:237], v[76:79]
	v_mfma_f32_16x16x32_bf16 v[72:75], v[188:191], v[234:237], v[72:75]
	v_mfma_f32_16x16x32_bf16 v[68:71], v[180:183], v[242:245], v[68:71]
	v_mfma_f32_16x16x32_bf16 v[64:67], v[188:191], v[242:245], v[64:67]
	s_setprio 0
	s_barrier
	s_add_i32 s56, s56, s63
	s_mov_b32 m0, s56
	ds_read_b128 v[192:195], v145 offset:16384
	ds_read_b128 v[196:199], v145 offset:17408
	ds_read_b128 v[222:225], v145 offset:18432
	ds_read_b128 v[226:229], v145 offset:19456
	ds_read_b128 v[230:233], v145 offset:20480
	ds_read_b128 v[234:237], v145 offset:21504
	ds_read_b128 v[238:241], v145 offset:22528
	ds_read_b128 v[242:245], v145 offset:23552
	global_load_lds_dwordx4 v130, s[4:5]
	s_add_i32 m0, s56, 0x2000
	s_add_u32 s56, s4, 0x80000
	s_addc_u32 s57, s5, 0
	s_add_i32 vcc_lo, vcc_lo, s63
	global_load_lds_dwordx4 v134, s[4:5]
	s_mov_b32 m0, vcc_lo
	s_nop 0
	global_load_lds_dwordx4 v130, s[56:57]
	s_add_i32 m0, vcc_lo, 0x2000
	s_nop 0
	global_load_lds_dwordx4 v134, s[56:57]
	s_mov_b32 m0, s89
	s_nop 0
	global_load_lds_dwordx4 v128, s[52:53]
	s_mov_b32 m0, s91
	s_nop 0
	global_load_lds_dwordx4 v132, s[52:53]
	s_add_u32 s98, s52, 0x80
	s_addc_u32 s99, s53, 0
	s_waitcnt vmcnt(8)
	s_waitcnt lgkmcnt(0)
	s_barrier
; #define PG8_STAGE(bufoff, gbase, voff) do { _Pragma("unroll") for (int _i = 0; _i < 2; ++_i) \
;         __builtin_amdgcn_global_load_lds((const unsigned*)((const char*)(gbase) + (voff)[_i]), (PG8_LAS unsigned*)(lds + (bufoff) + ldsw + _i * 8192), 16, 0, 0); } while (0)
; #define PG8_LDA(dst, b, h) do { _Pragma("unroll") for (int m = 0; m < 4; ++m) _Pragma("unroll") for (int k = 0; k < 2; ++k) dst[m][k] = *(const PG8_LAS bf16x8*)(lds + PG8_SA(b, h) + aoff + m * 2048 + k * 1024); } while (0)
; #define PG8_LDB(dst, b, h) do { _Pragma("unroll") for (int n = 0; n < 2; ++n) _Pragma("unroll") for (int k = 0; k < 2; ++k) dst[n][k] = *(const PG8_LAS bf16x8*)(lds + PG8_SB(b, h) + boff + n * 2048 + k * 1024); } while (0)
; #define PG8_MMA(ai, bj, At, Bt) do { __builtin_amdgcn_s_setprio(1); _Pragma("unroll") for (int m = 0; m < 4; ++m) _Pragma("unroll") for (int n = 0; n < 2; ++n) _Pragma("unroll") for (int k = 0; k < 2; ++k) \
;         acc[ai][bj][m][n] = __builtin_amdgcn_mfma_f32_16x16x32_bf16(Bt[n][k], At[m][k], acc[ai][bj][m][n], 0, 0, 0); __builtin_amdgcn_s_setprio(0); } while (0)
; #define PG8_WAIT_V(n) asm volatile("s_waitcnt vmcnt(" #n ")" ::: "memory")
; #define PG8_WAIT_L(n) asm volatile("s_waitcnt lgkmcnt(" #n ")" ::: "memory")
; #define PG8_BAR __builtin_amdgcn_s_barrier()
; #define PG8_SCHED __builtin_amdgcn_sched_barrier(0)
; template <class Epi, class Sched, bool ALIGN_EPI = false, bool SP2 = false>
; __device__ __forceinline__ void gemm_phase(PG8_LAS unsigned char* lds, const Gemm g, const Sched& S, const Epi& E) {
;     ...
;             PG8_WAIT_V(8); PG8_WAIT_L(0); PG8_BAR; PG8_MMA(1, 0, At, B0); PG8_MMA(1, 1, At, B1); PG8_BAR; PG8_SCHED;
;             PG8_LDB(B0, 1, 0); PG8_LDB(B1, 1, 1); PG8_SCHED; PG8_LDA(At, 1, 0); PG8_STAGE(PG8_SA(0, 1), a2 + hstep, voffA);
;             PG8_WAIT_V(8); PG8_WAIT_L(0); PG8_BAR; PG8_MMA(0, 0, At, B0); PG8_MMA(0, 1, At, B1); PG8_BAR; PG8_SCHED;
	s_setprio 1
	s_waitcnt lgkmcnt(0)
	v_mfma_f32_16x16x32_bf16 v[60:63], v[154:157], v[192:195], v[60:63]
	v_mfma_f32_16x16x32_bf16 v[56:59], v[168:171], v[192:195], v[56:59]
	v_mfma_f32_16x16x32_bf16 v[52:55], v[154:157], v[222:225], v[52:55]
	v_mfma_f32_16x16x32_bf16 v[48:51], v[168:171], v[222:225], v[48:51]
	v_mfma_f32_16x16x32_bf16 v[44:47], v[154:157], v[230:233], v[44:47]
	v_mfma_f32_16x16x32_bf16 v[40:43], v[168:171], v[230:233], v[40:43]
	v_mfma_f32_16x16x32_bf16 v[36:39], v[154:157], v[238:241], v[36:39]
	v_mfma_f32_16x16x32_bf16 v[32:35], v[168:171], v[238:241], v[32:35]
	v_mfma_f32_16x16x32_bf16 v[60:63], v[164:167], v[196:199], v[60:63]
	v_mfma_f32_16x16x32_bf16 v[56:59], v[172:175], v[196:199], v[56:59]
	v_mfma_f32_16x16x32_bf16 v[52:55], v[164:167], v[226:229], v[52:55]
	v_mfma_f32_16x16x32_bf16 v[48:51], v[172:175], v[226:229], v[48:51]
	v_mfma_f32_16x16x32_bf16 v[44:47], v[164:167], v[234:237], v[44:47]
	v_mfma_f32_16x16x32_bf16 v[40:43], v[172:175], v[234:237], v[40:43]
	v_mfma_f32_16x16x32_bf16 v[36:39], v[164:167], v[242:245], v[36:39]
	v_mfma_f32_16x16x32_bf16 v[32:35], v[172:175], v[242:245], v[32:35]
	s_setprio 0
	s_setprio 1
	v_mfma_f32_16x16x32_bf16 v[28:31], v[176:179], v[192:195], v[28:31]
	v_mfma_f32_16x16x32_bf16 v[24:27], v[184:187], v[192:195], v[24:27]
	v_mfma_f32_16x16x32_bf16 v[20:23], v[176:179], v[222:225], v[20:23]
	v_mfma_f32_16x16x32_bf16 v[16:19], v[184:187], v[222:225], v[16:19]
	v_mfma_f32_16x16x32_bf16 v[12:15], v[176:179], v[230:233], v[12:15]
	v_mfma_f32_16x16x32_bf16 v[8:11], v[184:187], v[230:233], v[8:11]
	v_mfma_f32_16x16x32_bf16 v[4:7], v[176:179], v[238:241], v[4:7]
	v_mfma_f32_16x16x32_bf16 v[0:3], v[184:187], v[238:241], v[0:3]
	v_mfma_f32_16x16x32_bf16 v[28:31], v[180:183], v[196:199], v[28:31]
	v_mfma_f32_16x16x32_bf16 v[24:27], v[188:191], v[196:199], v[24:27]
	v_mfma_f32_16x16x32_bf16 v[20:23], v[180:183], v[226:229], v[20:23]
	v_mfma_f32_16x16x32_bf16 v[16:19], v[188:191], v[226:229], v[16:19]
	v_mfma_f32_16x16x32_bf16 v[12:15], v[180:183], v[234:237], v[12:15]
	v_mfma_f32_16x16x32_bf16 v[8:11], v[188:191], v[234:237], v[8:11]
	v_mfma_f32_16x16x32_bf16 v[4:7], v[180:183], v[242:245], v[4:7]
	v_mfma_f32_16x16x32_bf16 v[0:3], v[188:191], v[242:245], v[0:3]
	s_setprio 0
	s_barrier
	s_add_i32 s56, 0, 0x18000
	v_add_u32_e32 v160, s56, v139
	s_add_i32 s57, 0, 0x1c000
	ds_read_b128 v[154:157], v160
	ds_read_b128 v[164:167], v160 offset:1024
	ds_read_b128 v[168:171], v160 offset:2048
	ds_read_b128 v[172:175], v160 offset:3072
	v_add_u32_e32 v160, s57, v139
	ds_read_b128 v[176:179], v160
	ds_read_b128 v[180:183], v160 offset:1024
	ds_read_b128 v[184:187], v160 offset:2048
	ds_read_b128 v[188:191], v160 offset:3072
	s_add_u32 s52, s52, 0x80000
	s_addc_u32 s53, s53, 0
	s_mov_b32 m0, s12
	ds_read_b128 v[192:195], v145 offset:32768
	ds_read_b128 v[196:199], v145 offset:33792
	ds_read_b128 v[222:225], v145 offset:34816
	ds_read_b128 v[226:229], v145 offset:35840
	ds_read_b128 v[230:233], v145 offset:36864
	ds_read_b128 v[234:237], v145 offset:37888
	ds_read_b128 v[238:241], v145 offset:38912
	ds_read_b128 v[242:245], v145 offset:39936
	global_load_lds_dwordx4 v128, s[52:53]
	s_mov_b32 m0, s13
	s_nop 0
	global_load_lds_dwordx4 v132, s[52:53]
	s_waitcnt vmcnt(8)
	s_waitcnt lgkmcnt(0)
	s_barrier
	s_setprio 1
	s_waitcnt lgkmcnt(0)
	v_mfma_f32_16x16x32_bf16 v[124:127], v[154:157], v[192:195], v[124:127]
	v_mfma_f32_16x16x32_bf16 v[120:123], v[168:171], v[192:195], v[120:123]
	v_mfma_f32_16x16x32_bf16 v[116:119], v[154:157], v[222:225], v[116:119]
	v_mfma_f32_16x16x32_bf16 v[112:115], v[168:171], v[222:225], v[112:115]
	v_mfma_f32_16x16x32_bf16 v[108:111], v[154:157], v[230:233], v[108:111]
	v_mfma_f32_16x16x32_bf16 v[104:107], v[168:171], v[230:233], v[104:107]
	v_mfma_f32_16x16x32_bf16 v[100:103], v[154:157], v[238:241], v[100:103]
	v_mfma_f32_16x16x32_bf16 v[96:99], v[168:171], v[238:241], v[96:99]
	v_mfma_f32_16x16x32_bf16 v[124:127], v[164:167], v[196:199], v[124:127]
	v_mfma_f32_16x16x32_bf16 v[120:123], v[172:175], v[196:199], v[120:123]
	v_mfma_f32_16x16x32_bf16 v[116:119], v[164:167], v[226:229], v[116:119]
	v_mfma_f32_16x16x32_bf16 v[112:115], v[172:175], v[226:229], v[112:115]
	v_mfma_f32_16x16x32_bf16 v[108:111], v[164:167], v[234:237], v[108:111]
	v_mfma_f32_16x16x32_bf16 v[104:107], v[172:175], v[234:237], v[104:107]
	v_mfma_f32_16x16x32_bf16 v[100:103], v[164:167], v[242:245], v[100:103]
	v_mfma_f32_16x16x32_bf16 v[96:99], v[172:175], v[242:245], v[96:99]
	s_setprio 0
	s_setprio 1
	v_mfma_f32_16x16x32_bf16 v[92:95], v[176:179], v[192:195], v[92:95]
	v_mfma_f32_16x16x32_bf16 v[88:91], v[184:187], v[192:195], v[88:91]
	v_mfma_f32_16x16x32_bf16 v[84:87], v[176:179], v[222:225], v[84:87]
	v_mfma_f32_16x16x32_bf16 v[80:83], v[184:187], v[222:225], v[80:83]
	v_mfma_f32_16x16x32_bf16 v[76:79], v[176:179], v[230:233], v[76:79]
	v_mfma_f32_16x16x32_bf16 v[72:75], v[184:187], v[230:233], v[72:75]
	v_mfma_f32_16x16x32_bf16 v[68:71], v[176:179], v[238:241], v[68:71]
	v_mfma_f32_16x16x32_bf16 v[64:67], v[184:187], v[238:241], v[64:67]
	v_mfma_f32_16x16x32_bf16 v[92:95], v[180:183], v[196:199], v[92:95]
	v_mfma_f32_16x16x32_bf16 v[88:91], v[188:191], v[196:199], v[88:91]
	v_mfma_f32_16x16x32_bf16 v[84:87], v[180:183], v[226:229], v[84:87]
	v_mfma_f32_16x16x32_bf16 v[80:83], v[188:191], v[226:229], v[80:83]
	v_mfma_f32_16x16x32_bf16 v[76:79], v[180:183], v[234:237], v[76:79]
	v_mfma_f32_16x16x32_bf16 v[72:75], v[188:191], v[234:237], v[72:75]
	v_mfma_f32_16x16x32_bf16 v[68:71], v[180:183], v[242:245], v[68:71]
	v_mfma_f32_16x16x32_bf16 v[64:67], v[188:191], v[242:245], v[64:67]
	s_setprio 0
	s_barrier
; #define PG8_STAGE(bufoff, gbase, voff) do { _Pragma("unroll") for (int _i = 0; _i < 2; ++_i) \
;         __builtin_amdgcn_global_load_lds((const unsigned*)((const char*)(gbase) + (voff)[_i]), (PG8_LAS unsigned*)(lds + (bufoff) + ldsw + _i * 8192), 16, 0, 0); } while (0)
; #define PG8_LDA(dst, b, h) do { _Pragma("unroll") for (int m = 0; m < 4; ++m) _Pragma("unroll") for (int k = 0; k < 2; ++k) dst[m][k] = *(const PG8_LAS bf16x8*)(lds + PG8_SA(b, h) + aoff + m * 2048 + k * 1024); } while (0)
; #define PG8_MMA(ai, bj, At, Bt) do { __builtin_amdgcn_s_setprio(1); _Pragma("unroll") for (int m = 0; m < 4; ++m) _Pragma("unroll") for (int n = 0; n < 2; ++n) _Pragma("unroll") for (int k = 0; k < 2; ++k) \
;         acc[ai][bj][m][n] = __builtin_amdgcn_mfma_f32_16x16x32_bf16(Bt[n][k], At[m][k], acc[ai][bj][m][n], 0, 0, 0); __builtin_amdgcn_s_setprio(0); } while (0)
; #define PG8_WAIT_V(n) asm volatile("s_waitcnt vmcnt(" #n ")" ::: "memory")
; #define PG8_WAIT_L(n) asm volatile("s_waitcnt lgkmcnt(" #n ")" ::: "memory")
; #define PG8_BAR __builtin_amdgcn_s_barrier()
; #define PG8_SCHED __builtin_amdgcn_sched_barrier(0)
; template <class Epi, class Sched, bool ALIGN_EPI = false, bool SP2 = false>
; __device__ __forceinline__ void gemm_phase(PG8_LAS unsigned char* lds, const Gemm g, const Sched& S, const Epi& E) {
;     ...
;             PG8_LDA(At, 1, 1); PG8_STAGE(PG8_SB(1, 0), b3, voffB); PG8_STAGE(PG8_SB(1, 1), b3 + hstep, voffB); PG8_STAGE(PG8_SA(1, 0), a3, voffA);
;             PG8_WAIT_V(8); PG8_WAIT_L(0); PG8_BAR; PG8_MMA(1, 0, At, B0); PG8_MMA(1, 1, At, B1); PG8_BAR; PG8_SCHED;
	s_add_i32 s52, s56, s63
	s_mov_b32 m0, s52
	ds_read_b128 v[192:195], v145 offset:49152
	ds_read_b128 v[196:199], v145 offset:50176
	ds_read_b128 v[222:225], v145 offset:51200
	ds_read_b128 v[226:229], v145 offset:52224
	ds_read_b128 v[230:233], v145 offset:53248
	ds_read_b128 v[234:237], v145 offset:54272
	ds_read_b128 v[238:241], v145 offset:55296
	ds_read_b128 v[242:245], v145 offset:56320
	s_add_u32 s4, s4, 0x80
	s_addc_u32 s5, s5, 0
	global_load_lds_dwordx4 v130, s[4:5]
	s_add_i32 m0, s52, 0x2000
	s_add_i32 s52, s57, s63
	global_load_lds_dwordx4 v134, s[4:5]
	s_add_u32 s4, s4, 0x80000
	s_addc_u32 s5, s5, 0
	s_mov_b32 m0, s52
	s_nop 0
	global_load_lds_dwordx4 v130, s[4:5]
	s_add_i32 m0, s52, 0x2000
	s_nop 0
	global_load_lds_dwordx4 v134, s[4:5]
	s_mov_b32 m0, s78
	s_nop 0
	global_load_lds_dwordx4 v128, s[98:99]
	s_mov_b32 m0, s79
	s_nop 0
	global_load_lds_dwordx4 v132, s[98:99]
	s_waitcnt vmcnt(8)
	s_waitcnt lgkmcnt(0)
	s_barrier
	s_setprio 1
	s_waitcnt lgkmcnt(0)
	v_mfma_f32_16x16x32_bf16 v[60:63], v[154:157], v[192:195], v[60:63]
	v_mfma_f32_16x16x32_bf16 v[56:59], v[168:171], v[192:195], v[56:59]
	v_mfma_f32_16x16x32_bf16 v[52:55], v[154:157], v[222:225], v[52:55]
	v_mfma_f32_16x16x32_bf16 v[48:51], v[168:171], v[222:225], v[48:51]
	v_mfma_f32_16x16x32_bf16 v[44:47], v[154:157], v[230:233], v[44:47]
	v_mfma_f32_16x16x32_bf16 v[40:43], v[168:171], v[230:233], v[40:43]
	v_mfma_f32_16x16x32_bf16 v[36:39], v[154:157], v[238:241], v[36:39]
	v_mfma_f32_16x16x32_bf16 v[32:35], v[168:171], v[238:241], v[32:35]
	v_mfma_f32_16x16x32_bf16 v[60:63], v[164:167], v[196:199], v[60:63]
	v_mfma_f32_16x16x32_bf16 v[56:59], v[172:175], v[196:199], v[56:59]
	v_mfma_f32_16x16x32_bf16 v[52:55], v[164:167], v[226:229], v[52:55]
	v_mfma_f32_16x16x32_bf16 v[48:51], v[172:175], v[226:229], v[48:51]
	v_mfma_f32_16x16x32_bf16 v[44:47], v[164:167], v[234:237], v[44:47]
	v_mfma_f32_16x16x32_bf16 v[40:43], v[172:175], v[234:237], v[40:43]
	v_mfma_f32_16x16x32_bf16 v[36:39], v[164:167], v[242:245], v[36:39]
	v_mfma_f32_16x16x32_bf16 v[32:35], v[172:175], v[242:245], v[32:35]
	s_setprio 0
	s_setprio 1
	v_mfma_f32_16x16x32_bf16 v[28:31], v[176:179], v[192:195], v[28:31]
	v_mfma_f32_16x16x32_bf16 v[24:27], v[184:187], v[192:195], v[24:27]
	v_mfma_f32_16x16x32_bf16 v[20:23], v[176:179], v[222:225], v[20:23]
	v_mfma_f32_16x16x32_bf16 v[16:19], v[184:187], v[222:225], v[16:19]
	v_mfma_f32_16x16x32_bf16 v[12:15], v[176:179], v[230:233], v[12:15]
	v_mfma_f32_16x16x32_bf16 v[8:11], v[184:187], v[230:233], v[8:11]
	v_mfma_f32_16x16x32_bf16 v[4:7], v[176:179], v[238:241], v[4:7]
	v_mfma_f32_16x16x32_bf16 v[0:3], v[184:187], v[238:241], v[0:3]
	v_mfma_f32_16x16x32_bf16 v[28:31], v[180:183], v[196:199], v[28:31]
	v_mfma_f32_16x16x32_bf16 v[24:27], v[188:191], v[196:199], v[24:27]
	v_mfma_f32_16x16x32_bf16 v[20:23], v[180:183], v[226:229], v[20:23]
	v_mfma_f32_16x16x32_bf16 v[16:19], v[188:191], v[226:229], v[16:19]
	v_mfma_f32_16x16x32_bf16 v[12:15], v[180:183], v[234:237], v[12:15]
	v_mfma_f32_16x16x32_bf16 v[8:11], v[188:191], v[234:237], v[8:11]
	v_mfma_f32_16x16x32_bf16 v[4:7], v[180:183], v[242:245], v[4:7]
	v_mfma_f32_16x16x32_bf16 v[0:3], v[188:191], v[242:245], v[0:3]
	s_setprio 0
	s_barrier
	s_add_i32 s55, s55, 2
	s_add_u32 s14, s14, 0x100
	s_addc_u32 s15, s15, 0
	s_add_u32 s45, s45, 0x100
	s_addc_u32 s54, s54, 0
	s_cmp_gt_u32 s55, 29
	s_cbranch_scc0 .LBB0_322
	s_and_b64 vcc, exec, s[82:83]
	s_cbranch_vccz .LBB0_325
	s_barrier

; #define PG8_STAGE(bufoff, gbase, voff) do { _Pragma("unroll") for (int _i = 0; _i < 2; ++_i) \
;         __builtin_amdgcn_global_load_lds((const unsigned*)((const char*)(gbase) + (voff)[_i]), (PG8_LAS unsigned*)(lds + (bufoff) + ldsw + _i * 8192), 16, 0, 0); } while (0)
; #define PG8_LDA(dst, b, h) do { _Pragma("unroll") for (int m = 0; m < 4; ++m) _Pragma("unroll") for (int k = 0; k < 2; ++k) dst[m][k] = *(const PG8_LAS bf16x8*)(lds + PG8_SA(b, h) + aoff + m * 2048 + k * 1024); } while (0)
; #define PG8_LDB(dst, b, h) do { _Pragma("unroll") for (int n = 0; n < 2; ++n) _Pragma("unroll") for (int k = 0; k < 2; ++k) dst[n][k] = *(const PG8_LAS bf16x8*)(lds + PG8_SB(b, h) + boff + n * 2048 + k * 1024); } while (0)
; #define PG8_MMA(ai, bj, At, Bt) do { __builtin_amdgcn_s_setprio(1); _Pragma("unroll") for (int m = 0; m < 4; ++m) _Pragma("unroll") for (int n = 0; n < 2; ++n) _Pragma("unroll") for (int k = 0; k < 2; ++k) \
;         acc[ai][bj][m][n] = __builtin_amdgcn_mfma_f32_16x16x32_bf16(Bt[n][k], At[m][k], acc[ai][bj][m][n], 0, 0, 0); __builtin_amdgcn_s_setprio(0); } while (0)
; #define PG8_WAIT_V(n) asm volatile("s_waitcnt vmcnt(" #n ")" ::: "memory")
; #define PG8_WAIT_L(n) asm volatile("s_waitcnt lgkmcnt(" #n ")" ::: "memory")
; template <class Epi, class Sched, bool ALIGN_EPI = false, bool SP2 = false>
; __device__ __forceinline__ void gemm_phase(PG8_LAS unsigned char* lds, const Gemm g, const Sched& S, const Epi& E) {
;     ...
;             const bool last = (t == nt - 2);
;             const char* a1 = cA + (size_t)(t + 1) * kstep;
;             const char* a2 = last ? nA : cA + (size_t)(t + 2) * kstep; const char* b2 = last ? nB : cB + (size_t)(t + 2) * kstep;
;             const char* a3 = a2 + kstep; const char* b3 = b2 + kstep;
;             if (last && has_next) S.a_ready(nxt);
;             if constexpr (SP2) {
;             PG8_LDB(B0, 0, 0); PG8_LDB(B1, 0, 1); PG8_SCHED; PG8_LDA(At, 0, 0); PG8_STAGE(PG8_SA(1, 1), a1 + hstep, voffA);
;             PG8_WAIT_V(8); PG8_WAIT_L(0); PG8_BAR; PG8_MMA(0, 0, At, B0); PG8_MMA(0, 1, At, B1); PG8_BAR; PG8_SCHED;
;             PG8_LDA(At, 0, 1); PG8_STAGE(PG8_SB(0, 0), b2, voffB); PG8_STAGE(PG8_SB(0, 1), b2 + hstep, voffB); PG8_STAGE(PG8_SA(0, 0), a2, voffA);
;             PG8_WAIT_V(8); PG8_WAIT_L(0); PG8_BAR; PG8_MMA(1, 0, At, B0); PG8_MMA(1, 1, At, B1); PG8_BAR; PG8_SCHED;
.LBB0_849:
	s_add_u32 s4, s70, 0xfff80080
	s_addc_u32 s5, s71, -1
	s_add_i32 s76, 0, 0x10000
	s_cmp_eq_u32 s75, 28
	s_cselect_b32 s53, s11, s5
	s_cselect_b32 s52, s63, s4
	v_add_u32_e32 v138, s76, v141
	s_cselect_b32 s5, s13, s74
	s_cselect_b32 s4, s72, s73
	s_add_i32 s78, 0, 0x14000
	ds_read_b128 v[144:147], v138
	ds_read_b128 v[148:151], v138 offset:1024
	ds_read_b128 v[152:155], v138 offset:2048
	ds_read_b128 v[156:159], v138 offset:3072
	v_add_u32_e32 v138, s78, v141
	ds_read_b128 v[164:167], v138
	ds_read_b128 v[168:171], v138 offset:1024
	ds_read_b128 v[172:175], v138 offset:2048
	ds_read_b128 v[176:179], v138 offset:3072
	s_add_i32 m0, s51, 0xc000
	ds_read_b128 v[180:183], v143
	ds_read_b128 v[184:187], v143 offset:1024
	ds_read_b128 v[188:191], v143 offset:2048
	ds_read_b128 v[192:195], v143 offset:3072
	ds_read_b128 v[196:199], v143 offset:4096
	ds_read_b128 v[222:225], v143 offset:5120
	ds_read_b128 v[226:229], v143 offset:6144
	ds_read_b128 v[230:233], v143 offset:7168
	global_load_lds_dwordx4 v134, s[70:71]
	s_add_i32 m0, s51, 0xe000
	s_nop 0
	global_load_lds_dwordx4 v136, s[70:71]
	s_waitcnt vmcnt(8)
	s_waitcnt lgkmcnt(0)
	s_barrier
	s_setprio 1
	s_waitcnt lgkmcnt(0)
	v_mfma_f32_16x16x32_bf16 v[124:127], v[144:147], v[180:183], v[124:127]
	v_mfma_f32_16x16x32_bf16 v[116:119], v[152:155], v[180:183], v[116:119]
	v_mfma_f32_16x16x32_bf16 v[108:111], v[144:147], v[188:191], v[108:111]
	v_mfma_f32_16x16x32_bf16 v[100:103], v[152:155], v[188:191], v[100:103]
	v_mfma_f32_16x16x32_bf16 v[92:95], v[144:147], v[196:199], v[92:95]
	v_mfma_f32_16x16x32_bf16 v[84:87], v[152:155], v[196:199], v[84:87]
	v_mfma_f32_16x16x32_bf16 v[76:79], v[144:147], v[226:229], v[76:79]
	v_mfma_f32_16x16x32_bf16 v[68:71], v[152:155], v[226:229], v[68:71]
	v_mfma_f32_16x16x32_bf16 v[124:127], v[148:151], v[184:187], v[124:127]
	v_mfma_f32_16x16x32_bf16 v[116:119], v[156:159], v[184:187], v[116:119]
	v_mfma_f32_16x16x32_bf16 v[108:111], v[148:151], v[192:195], v[108:111]
	v_mfma_f32_16x16x32_bf16 v[100:103], v[156:159], v[192:195], v[100:103]
	v_mfma_f32_16x16x32_bf16 v[92:95], v[148:151], v[222:225], v[92:95]
	v_mfma_f32_16x16x32_bf16 v[84:87], v[156:159], v[222:225], v[84:87]
	v_mfma_f32_16x16x32_bf16 v[76:79], v[148:151], v[230:233], v[76:79]
	v_mfma_f32_16x16x32_bf16 v[68:71], v[156:159], v[230:233], v[68:71]
	s_setprio 0
	s_setprio 1
	v_mfma_f32_16x16x32_bf16 v[120:123], v[164:167], v[180:183], v[120:123]
	v_mfma_f32_16x16x32_bf16 v[112:115], v[172:175], v[180:183], v[112:115]
	v_mfma_f32_16x16x32_bf16 v[104:107], v[164:167], v[188:191], v[104:107]
	v_mfma_f32_16x16x32_bf16 v[96:99], v[172:175], v[188:191], v[96:99]
	v_mfma_f32_16x16x32_bf16 v[88:91], v[164:167], v[196:199], v[88:91]
	v_mfma_f32_16x16x32_bf16 v[80:83], v[172:175], v[196:199], v[80:83]
	v_mfma_f32_16x16x32_bf16 v[72:75], v[164:167], v[226:229], v[72:75]
	v_mfma_f32_16x16x32_bf16 v[64:67], v[172:175], v[226:229], v[64:67]
	v_mfma_f32_16x16x32_bf16 v[120:123], v[168:171], v[184:187], v[120:123]
	v_mfma_f32_16x16x32_bf16 v[112:115], v[176:179], v[184:187], v[112:115]
	v_mfma_f32_16x16x32_bf16 v[104:107], v[168:171], v[192:195], v[104:107]
	v_mfma_f32_16x16x32_bf16 v[96:99], v[176:179], v[192:195], v[96:99]
	v_mfma_f32_16x16x32_bf16 v[88:91], v[168:171], v[222:225], v[88:91]
	v_mfma_f32_16x16x32_bf16 v[80:83], v[176:179], v[222:225], v[80:83]
	v_mfma_f32_16x16x32_bf16 v[72:75], v[168:171], v[230:233], v[72:75]
	v_mfma_f32_16x16x32_bf16 v[64:67], v[176:179], v[230:233], v[64:67]
	s_setprio 0
	s_barrier
	s_add_i32 s76, s76, s24
	s_mov_b32 m0, s76
	ds_read_b128 v[180:183], v143 offset:16384
	ds_read_b128 v[184:187], v143 offset:17408
	ds_read_b128 v[188:191], v143 offset:18432
	ds_read_b128 v[192:195], v143 offset:19456
	ds_read_b128 v[196:199], v143 offset:20480
	ds_read_b128 v[222:225], v143 offset:21504
	ds_read_b128 v[226:229], v143 offset:22528
	ds_read_b128 v[230:233], v143 offset:23552
	global_load_lds_dwordx4 v160, s[4:5]
	s_add_i32 m0, s76, 0x2000
	s_add_u32 s76, s4, 0x80000
	s_addc_u32 s77, s5, 0
	s_add_i32 s78, s78, s24
	global_load_lds_dwordx4 v128, s[4:5]
	s_mov_b32 m0, s78
	s_nop 0
	global_load_lds_dwordx4 v160, s[76:77]
	s_add_i32 m0, s78, 0x2000
	s_nop 0
	global_load_lds_dwordx4 v128, s[76:77]
	s_mov_b32 m0, s51
	s_nop 0
	global_load_lds_dwordx4 v132, s[52:53]
	s_mov_b32 m0, s55
	s_nop 0
	global_load_lds_dwordx4 v130, s[52:53]
	s_add_u32 s98, s52, 0x80
	s_addc_u32 s99, s53, 0
	s_waitcnt vmcnt(8)
	s_waitcnt lgkmcnt(0)
	s_barrier
	s_setprio 1
	s_waitcnt lgkmcnt(0)
	v_mfma_f32_16x16x32_bf16 v[60:63], v[144:147], v[180:183], v[60:63]
	v_mfma_f32_16x16x32_bf16 v[52:55], v[152:155], v[180:183], v[52:55]
	v_mfma_f32_16x16x32_bf16 v[44:47], v[144:147], v[188:191], v[44:47]
	v_mfma_f32_16x16x32_bf16 v[36:39], v[152:155], v[188:191], v[36:39]
	v_mfma_f32_16x16x32_bf16 v[28:31], v[144:147], v[196:199], v[28:31]
	v_mfma_f32_16x16x32_bf16 v[20:23], v[152:155], v[196:199], v[20:23]
	v_mfma_f32_16x16x32_bf16 v[12:15], v[144:147], v[226:229], v[12:15]
	v_mfma_f32_16x16x32_bf16 v[4:7], v[152:155], v[226:229], v[4:7]
	v_mfma_f32_16x16x32_bf16 v[60:63], v[148:151], v[184:187], v[60:63]
	v_mfma_f32_16x16x32_bf16 v[52:55], v[156:159], v[184:187], v[52:55]
	v_mfma_f32_16x16x32_bf16 v[44:47], v[148:151], v[192:195], v[44:47]
	v_mfma_f32_16x16x32_bf16 v[36:39], v[156:159], v[192:195], v[36:39]
	v_mfma_f32_16x16x32_bf16 v[28:31], v[148:151], v[222:225], v[28:31]
	v_mfma_f32_16x16x32_bf16 v[20:23], v[156:159], v[222:225], v[20:23]
	v_mfma_f32_16x16x32_bf16 v[12:15], v[148:151], v[230:233], v[12:15]
	v_mfma_f32_16x16x32_bf16 v[4:7], v[156:159], v[230:233], v[4:7]
	s_setprio 0
	s_setprio 1
	v_mfma_f32_16x16x32_bf16 v[56:59], v[164:167], v[180:183], v[56:59]
	v_mfma_f32_16x16x32_bf16 v[48:51], v[172:175], v[180:183], v[48:51]
	v_mfma_f32_16x16x32_bf16 v[40:43], v[164:167], v[188:191], v[40:43]
	v_mfma_f32_16x16x32_bf16 v[32:35], v[172:175], v[188:191], v[32:35]
	v_mfma_f32_16x16x32_bf16 v[24:27], v[164:167], v[196:199], v[24:27]
	v_mfma_f32_16x16x32_bf16 v[16:19], v[172:175], v[196:199], v[16:19]
	v_mfma_f32_16x16x32_bf16 v[8:11], v[164:167], v[226:229], v[8:11]
	v_mfma_f32_16x16x32_bf16 v[0:3], v[172:175], v[226:229], v[0:3]
	v_mfma_f32_16x16x32_bf16 v[56:59], v[168:171], v[184:187], v[56:59]
	v_mfma_f32_16x16x32_bf16 v[48:51], v[176:179], v[184:187], v[48:51]
	v_mfma_f32_16x16x32_bf16 v[40:43], v[168:171], v[192:195], v[40:43]
	v_mfma_f32_16x16x32_bf16 v[32:35], v[176:179], v[192:195], v[32:35]
	v_mfma_f32_16x16x32_bf16 v[24:27], v[168:171], v[222:225], v[24:27]
	v_mfma_f32_16x16x32_bf16 v[16:19], v[176:179], v[222:225], v[16:19]
	v_mfma_f32_16x16x32_bf16 v[8:11], v[168:171], v[230:233], v[8:11]
	v_mfma_f32_16x16x32_bf16 v[0:3], v[176:179], v[230:233], v[0:3]
	s_setprio 0
	s_barrier
; #define PG8_STAGE(bufoff, gbase, voff) do { _Pragma("unroll") for (int _i = 0; _i < 2; ++_i) \
;         __builtin_amdgcn_global_load_lds((const unsigned*)((const char*)(gbase) + (voff)[_i]), (PG8_LAS unsigned*)(lds + (bufoff) + ldsw + _i * 8192), 16, 0, 0); } while (0)
; #define PG8_LDA(dst, b, h) do { _Pragma("unroll") for (int m = 0; m < 4; ++m) _Pragma("unroll") for (int k = 0; k < 2; ++k) dst[m][k] = *(const PG8_LAS bf16x8*)(lds + PG8_SA(b, h) + aoff + m * 2048 + k * 1024); } while (0)
; #define PG8_LDB(dst, b, h) do { _Pragma("unroll") for (int n = 0; n < 2; ++n) _Pragma("unroll") for (int k = 0; k < 2; ++k) dst[n][k] = *(const PG8_LAS bf16x8*)(lds + PG8_SB(b, h) + boff + n * 2048 + k * 1024); } while (0)
; #define PG8_MMA(ai, bj, At, Bt) do { __builtin_amdgcn_s_setprio(1); _Pragma("unroll") for (int m = 0; m < 4; ++m) _Pragma("unroll") for (int n = 0; n < 2; ++n) _Pragma("unroll") for (int k = 0; k < 2; ++k) \
;         acc[ai][bj][m][n] = __builtin_amdgcn_mfma_f32_16x16x32_bf16(Bt[n][k], At[m][k], acc[ai][bj][m][n], 0, 0, 0); __builtin_amdgcn_s_setprio(0); } while (0)
; #define PG8_WAIT_V(n) asm volatile("s_waitcnt vmcnt(" #n ")" ::: "memory")
; #define PG8_WAIT_L(n) asm volatile("s_waitcnt lgkmcnt(" #n ")" ::: "memory")
; #define PG8_BAR __builtin_amdgcn_s_barrier()
; #define PG8_SCHED __builtin_amdgcn_sched_barrier(0)
; template <class Epi, class Sched, bool ALIGN_EPI = false, bool SP2 = false>
; __device__ __forceinline__ void gemm_phase(PG8_LAS unsigned char* lds, const Gemm g, const Sched& S, const Epi& E) {
;     ...
;             PG8_LDB(B0, 1, 0); PG8_LDB(B1, 1, 1); PG8_SCHED; PG8_LDA(At, 1, 0); PG8_STAGE(PG8_SA(0, 1), a2 + hstep, voffA);
;             PG8_WAIT_V(8); PG8_WAIT_L(0); PG8_BAR; PG8_MMA(0, 0, At, B0); PG8_MMA(0, 1, At, B1); PG8_BAR; PG8_SCHED;
;             PG8_LDA(At, 1, 1); PG8_STAGE(PG8_SB(1, 0), b3, voffB); PG8_STAGE(PG8_SB(1, 1), b3 + hstep, voffB); PG8_STAGE(PG8_SA(1, 0), a3, voffA);
;             PG8_WAIT_V(8); PG8_WAIT_L(0); PG8_BAR; PG8_MMA(1, 0, At, B0); PG8_MMA(1, 1, At, B1); PG8_BAR; PG8_SCHED;
	s_add_i32 s76, 0, 0x18000
	s_add_i32 s77, 0, 0x1c000
	v_add_u32_e32 v156, s76, v141
	v_add_u32_e32 v163, s77, v141
	ds_read_b128 v[144:147], v156
	ds_read_b128 v[148:151], v156 offset:1024
	ds_read_b128 v[152:155], v156 offset:2048
	ds_read_b128 v[156:159], v156 offset:3072
	ds_read_b128 v[164:167], v163
	ds_read_b128 v[168:171], v163 offset:1024
	ds_read_b128 v[172:175], v163 offset:2048
	ds_read_b128 v[176:179], v163 offset:3072
	s_add_u32 s52, s52, 0x80000
	s_addc_u32 s53, s53, 0
	s_mov_b32 m0, s56
	ds_read_b128 v[180:183], v143 offset:32768
	ds_read_b128 v[184:187], v143 offset:33792
	ds_read_b128 v[188:191], v143 offset:34816
	ds_read_b128 v[192:195], v143 offset:35840
	ds_read_b128 v[196:199], v143 offset:36864
	ds_read_b128 v[222:225], v143 offset:37888
	ds_read_b128 v[226:229], v143 offset:38912
	ds_read_b128 v[230:233], v143 offset:39936
	global_load_lds_dwordx4 v132, s[52:53]
	s_mov_b32 m0, s57
	s_nop 0
	global_load_lds_dwordx4 v130, s[52:53]
	s_waitcnt vmcnt(8)
	s_waitcnt lgkmcnt(0)
	s_barrier
	s_setprio 1
	s_waitcnt lgkmcnt(0)
	v_mfma_f32_16x16x32_bf16 v[124:127], v[144:147], v[180:183], v[124:127]
	v_mfma_f32_16x16x32_bf16 v[116:119], v[152:155], v[180:183], v[116:119]
	v_mfma_f32_16x16x32_bf16 v[108:111], v[144:147], v[188:191], v[108:111]
	v_mfma_f32_16x16x32_bf16 v[100:103], v[152:155], v[188:191], v[100:103]
	v_mfma_f32_16x16x32_bf16 v[92:95], v[144:147], v[196:199], v[92:95]
	v_mfma_f32_16x16x32_bf16 v[84:87], v[152:155], v[196:199], v[84:87]
	v_mfma_f32_16x16x32_bf16 v[76:79], v[144:147], v[226:229], v[76:79]
	v_mfma_f32_16x16x32_bf16 v[68:71], v[152:155], v[226:229], v[68:71]
	v_mfma_f32_16x16x32_bf16 v[124:127], v[148:151], v[184:187], v[124:127]
	v_mfma_f32_16x16x32_bf16 v[116:119], v[156:159], v[184:187], v[116:119]
	v_mfma_f32_16x16x32_bf16 v[108:111], v[148:151], v[192:195], v[108:111]
	v_mfma_f32_16x16x32_bf16 v[100:103], v[156:159], v[192:195], v[100:103]
	v_mfma_f32_16x16x32_bf16 v[92:95], v[148:151], v[222:225], v[92:95]
	v_mfma_f32_16x16x32_bf16 v[84:87], v[156:159], v[222:225], v[84:87]
	v_mfma_f32_16x16x32_bf16 v[76:79], v[148:151], v[230:233], v[76:79]
	v_mfma_f32_16x16x32_bf16 v[68:71], v[156:159], v[230:233], v[68:71]
	s_setprio 0
	s_setprio 1
	v_mfma_f32_16x16x32_bf16 v[120:123], v[164:167], v[180:183], v[120:123]
	v_mfma_f32_16x16x32_bf16 v[112:115], v[172:175], v[180:183], v[112:115]
	v_mfma_f32_16x16x32_bf16 v[104:107], v[164:167], v[188:191], v[104:107]
	v_mfma_f32_16x16x32_bf16 v[96:99], v[172:175], v[188:191], v[96:99]
	v_mfma_f32_16x16x32_bf16 v[88:91], v[164:167], v[196:199], v[88:91]
	v_mfma_f32_16x16x32_bf16 v[80:83], v[172:175], v[196:199], v[80:83]
	v_mfma_f32_16x16x32_bf16 v[72:75], v[164:167], v[226:229], v[72:75]
	v_mfma_f32_16x16x32_bf16 v[64:67], v[172:175], v[226:229], v[64:67]
	v_mfma_f32_16x16x32_bf16 v[120:123], v[168:171], v[184:187], v[120:123]
	v_mfma_f32_16x16x32_bf16 v[112:115], v[176:179], v[184:187], v[112:115]
	v_mfma_f32_16x16x32_bf16 v[104:107], v[168:171], v[192:195], v[104:107]
	v_mfma_f32_16x16x32_bf16 v[96:99], v[176:179], v[192:195], v[96:99]
	v_mfma_f32_16x16x32_bf16 v[88:91], v[168:171], v[222:225], v[88:91]
	v_mfma_f32_16x16x32_bf16 v[80:83], v[176:179], v[222:225], v[80:83]
	v_mfma_f32_16x16x32_bf16 v[72:75], v[168:171], v[230:233], v[72:75]
	v_mfma_f32_16x16x32_bf16 v[64:67], v[176:179], v[230:233], v[64:67]
	s_setprio 0
	s_barrier
	s_add_i32 s52, s76, s24
	s_mov_b32 m0, s52
	ds_read_b128 v[180:183], v143 offset:49152
	ds_read_b128 v[184:187], v143 offset:50176
	ds_read_b128 v[188:191], v143 offset:51200
	ds_read_b128 v[192:195], v143 offset:52224
	ds_read_b128 v[196:199], v143 offset:53248
	ds_read_b128 v[222:225], v143 offset:54272
	ds_read_b128 v[226:229], v143 offset:55296
	ds_read_b128 v[230:233], v143 offset:56320
	s_add_u32 s4, s4, 0x80
	s_addc_u32 s5, s5, 0
	global_load_lds_dwordx4 v160, s[4:5]
	s_add_i32 m0, s52, 0x2000
	s_add_i32 s52, s77, s24
	global_load_lds_dwordx4 v128, s[4:5]
	s_add_u32 s4, s4, 0x80000
	s_addc_u32 s5, s5, 0
	s_mov_b32 m0, s52
	s_nop 0
	global_load_lds_dwordx4 v160, s[4:5]
	s_add_i32 m0, s52, 0x2000
	s_nop 0
	global_load_lds_dwordx4 v128, s[4:5]
	s_mov_b32 m0, s58
	s_nop 0
	global_load_lds_dwordx4 v132, s[98:99]
	s_mov_b32 m0, s59
	s_nop 0
	global_load_lds_dwordx4 v130, s[98:99]
	s_waitcnt vmcnt(8)
	s_waitcnt lgkmcnt(0)
	s_barrier
	s_setprio 1
	s_waitcnt lgkmcnt(0)
	v_mfma_f32_16x16x32_bf16 v[60:63], v[144:147], v[180:183], v[60:63]
	v_mfma_f32_16x16x32_bf16 v[52:55], v[152:155], v[180:183], v[52:55]
	v_mfma_f32_16x16x32_bf16 v[44:47], v[144:147], v[188:191], v[44:47]
	v_mfma_f32_16x16x32_bf16 v[36:39], v[152:155], v[188:191], v[36:39]
	v_mfma_f32_16x16x32_bf16 v[28:31], v[144:147], v[196:199], v[28:31]
	v_mfma_f32_16x16x32_bf16 v[20:23], v[152:155], v[196:199], v[20:23]
	v_mfma_f32_16x16x32_bf16 v[12:15], v[144:147], v[226:229], v[12:15]
	v_mfma_f32_16x16x32_bf16 v[4:7], v[152:155], v[226:229], v[4:7]
	v_mfma_f32_16x16x32_bf16 v[60:63], v[148:151], v[184:187], v[60:63]
	v_mfma_f32_16x16x32_bf16 v[52:55], v[156:159], v[184:187], v[52:55]
	v_mfma_f32_16x16x32_bf16 v[44:47], v[148:151], v[192:195], v[44:47]
	v_mfma_f32_16x16x32_bf16 v[36:39], v[156:159], v[192:195], v[36:39]
	v_mfma_f32_16x16x32_bf16 v[28:31], v[148:151], v[222:225], v[28:31]
	v_mfma_f32_16x16x32_bf16 v[20:23], v[156:159], v[222:225], v[20:23]
	v_mfma_f32_16x16x32_bf16 v[12:15], v[148:151], v[230:233], v[12:15]
	v_mfma_f32_16x16x32_bf16 v[4:7], v[156:159], v[230:233], v[4:7]
	s_setprio 0
	s_setprio 1
	v_mfma_f32_16x16x32_bf16 v[56:59], v[164:167], v[180:183], v[56:59]
	v_mfma_f32_16x16x32_bf16 v[48:51], v[172:175], v[180:183], v[48:51]
	v_mfma_f32_16x16x32_bf16 v[40:43], v[164:167], v[188:191], v[40:43]
	v_mfma_f32_16x16x32_bf16 v[32:35], v[172:175], v[188:191], v[32:35]
	v_mfma_f32_16x16x32_bf16 v[24:27], v[164:167], v[196:199], v[24:27]
	v_mfma_f32_16x16x32_bf16 v[16:19], v[172:175], v[196:199], v[16:19]
	v_mfma_f32_16x16x32_bf16 v[8:11], v[164:167], v[226:229], v[8:11]
	v_mfma_f32_16x16x32_bf16 v[0:3], v[172:175], v[226:229], v[0:3]
	v_mfma_f32_16x16x32_bf16 v[56:59], v[168:171], v[184:187], v[56:59]
	v_mfma_f32_16x16x32_bf16 v[48:51], v[176:179], v[184:187], v[48:51]
	v_mfma_f32_16x16x32_bf16 v[40:43], v[168:171], v[192:195], v[40:43]
	v_mfma_f32_16x16x32_bf16 v[32:35], v[176:179], v[192:195], v[32:35]
	v_mfma_f32_16x16x32_bf16 v[24:27], v[168:171], v[222:225], v[24:27]
	v_mfma_f32_16x16x32_bf16 v[16:19], v[176:179], v[222:225], v[16:19]
	v_mfma_f32_16x16x32_bf16 v[8:11], v[168:171], v[230:233], v[8:11]
	v_mfma_f32_16x16x32_bf16 v[0:3], v[176:179], v[230:233], v[0:3]
	s_setprio 0
	s_barrier
	s_add_i32 s75, s75, 2
	s_add_u32 s70, s70, 0x100
	s_addc_u32 s71, s71, 0
	s_add_u32 s73, s73, 0x100
	s_addc_u32 s74, s74, 0
	s_cmp_gt_u32 s75, 29
	s_cbranch_scc0 .LBB0_849
	s_and_b64 vcc, exec, s[8:9]
	s_cbranch_vccz .LBB0_852
	s_barrier
